# generated epilogues: plain v_rsq_f32 for rsqrt(x + 1e-6) (the argument is always a normal float, the denormal rescue path was never selected - identical bits)
# speedup vs baseline: 1.0924x; 1.0062x over previous
; DI void epi_slab(const GemmCfg c, const f32x16 (&acc)[4], float* sW, const float* rss, const size_t row0, const int g, const int lane,
;                  float* const g_h, u16* const g_hb, float* const g_out, const int final_out) {
;     ...
;   if (c.epi == EPI_SWIGLU) {
;     const int c4 = (ln_ & 15) * 4;
; #pragma unroll 2
;     for (int it = 0; it < 8; ++it) {
;       const int r = (ln_ >> 4) + 4 * it;
;       const float rs = rsqrtf(rss[r] * invK + 1e-6f);
;       f32x4 a = *(const f32x4*)(sW + r * 132 + c4);
;       f32x4 b = *(const f32x4*)(sW + r * 132 + 64 + c4);
;       float y[4];
; #pragma unroll
;       for (int e = 0; e < 4; ++e) { float av = a[e] * rs, bv = b[e] * rs; y[e] = av * __builtin_amdgcn_rcpf(1.f + __expf(-av)) * bv; }
;       *(u32x2*)(c.o16 + (row0 + r) * DFF + g * 64 + c4) = MK2(pack2(y[0], y[1]), pack2(y[2], y[3]));
;     }
.Lswg2_nopf:
	s_nop 0
	v_writelane_b32 v255, s9, 51
	s_mov_b64 s[8:9], 0
	s_waitcnt lgkmcnt(0)
	v_fmaak_f32 v226, v191, v226, 0x358637bd
	v_fmaak_f32 v227, v191, v227, 0x358637bd
	v_rsq_f32_e32 v226, v226
	v_rsq_f32_e32 v227, v227
	v_fmaak_f32 v228, v191, v228, 0x358637bd
	v_fmaak_f32 v229, v191, v229, 0x358637bd
	v_rsq_f32_e32 v228, v228
	v_rsq_f32_e32 v229, v229
	v_fmaak_f32 v230, v191, v230, 0x358637bd
	v_fmaak_f32 v231, v191, v231, 0x358637bd
	v_rsq_f32_e32 v230, v230
	v_rsq_f32_e32 v231, v231
	v_fmaak_f32 v232, v191, v232, 0x358637bd
	v_fmaak_f32 v233, v191, v233, 0x358637bd
	v_rsq_f32_e32 v232, v232
	v_rsq_f32_e32 v233, v233
	v_fmaak_f32 v234, v191, v234, 0x358637bd
	v_fmaak_f32 v235, v191, v235, 0x358637bd
	v_rsq_f32_e32 v234, v234
	v_rsq_f32_e32 v235, v235
	v_fmaak_f32 v236, v191, v236, 0x358637bd
	v_fmaak_f32 v237, v191, v237, 0x358637bd
	v_rsq_f32_e32 v236, v236
	v_rsq_f32_e32 v237, v237
	v_fmaak_f32 v238, v191, v238, 0x358637bd
	v_fmaak_f32 v239, v191, v239, 0x358637bd
	v_rsq_f32_e32 v238, v238
	v_rsq_f32_e32 v239, v239
	v_fmaak_f32 v240, v191, v240, 0x358637bd
	v_fmaak_f32 v241, v191, v241, 0x358637bd
	v_rsq_f32_e32 v240, v240
	v_rsq_f32_e32 v241, v241
	s_nop 0
	v_pk_mul_f32 v[64:65], v[64:65], v[226:227]
	v_pk_mul_f32 v[66:67], v[66:67], v[228:229]
	v_pk_mul_f32 v[80:81], v[80:81], v[226:227]
	v_pk_mul_f32 v[82:83], v[82:83], v[228:229]
	v_mul_f32_e32 v242, 0xbfb8aa3b, v64
	v_mul_f32_e32 v243, 0xbfb8aa3b, v65
	v_mul_f32_e32 v244, 0xbfb8aa3b, v66
	v_mul_f32_e32 v245, 0xbfb8aa3b, v67
	v_exp_f32_e32 v242, v242
	v_exp_f32_e32 v243, v243
	v_exp_f32_e32 v244, v244
	v_exp_f32_e32 v245, v245
	v_add_f32_e32 v242, 1.0, v242
	v_add_f32_e32 v243, 1.0, v243
	v_add_f32_e32 v244, 1.0, v244
	v_add_f32_e32 v245, 1.0, v245
	v_rcp_f32_e32 v242, v242
	v_rcp_f32_e32 v243, v243
	v_rcp_f32_e32 v244, v244
	v_rcp_f32_e32 v245, v245
	s_nop 0
	v_pk_mul_f32 v[64:65], v[64:65], v[242:243]
	v_pk_mul_f32 v[66:67], v[66:67], v[244:245]
	v_pk_mul_f32 v[64:65], v[80:81], v[64:65]
	v_pk_mul_f32 v[66:67], v[82:83], v[66:67]
	ds_write2_b32 v198, v64, v65 offset0:0 offset1:68
	ds_write2_b32 v198, v66, v67 offset0:136 offset1:204
	v_pk_mul_f32 v[68:69], v[68:69], v[226:227]
	v_pk_mul_f32 v[70:71], v[70:71], v[228:229]
	v_pk_mul_f32 v[84:85], v[84:85], v[226:227]
	v_pk_mul_f32 v[86:87], v[86:87], v[228:229]
	v_mul_f32_e32 v242, 0xbfb8aa3b, v68
	v_mul_f32_e32 v243, 0xbfb8aa3b, v69
	v_mul_f32_e32 v244, 0xbfb8aa3b, v70
	v_mul_f32_e32 v245, 0xbfb8aa3b, v71
	v_exp_f32_e32 v242, v242
	v_exp_f32_e32 v243, v243
	v_exp_f32_e32 v244, v244
	v_exp_f32_e32 v245, v245
	v_add_f32_e32 v242, 1.0, v242
	v_add_f32_e32 v243, 1.0, v243
	v_add_f32_e32 v244, 1.0, v244
	v_add_f32_e32 v245, 1.0, v245
	v_rcp_f32_e32 v242, v242
	v_rcp_f32_e32 v243, v243
	v_rcp_f32_e32 v244, v244
	v_rcp_f32_e32 v245, v245
	s_nop 0
	v_pk_mul_f32 v[68:69], v[68:69], v[242:243]
	v_pk_mul_f32 v[70:71], v[70:71], v[244:245]
	v_pk_mul_f32 v[68:69], v[84:85], v[68:69]
	v_pk_mul_f32 v[70:71], v[86:87], v[70:71]
	ds_write2_b32 v198, v68, v69 offset0:16 offset1:84
	ds_write2_b32 v198, v70, v71 offset0:152 offset1:220
	v_pk_mul_f32 v[72:73], v[72:73], v[226:227]
	v_pk_mul_f32 v[74:75], v[74:75], v[228:229]
	v_pk_mul_f32 v[88:89], v[88:89], v[226:227]
	v_pk_mul_f32 v[90:91], v[90:91], v[228:229]
	v_mul_f32_e32 v242, 0xbfb8aa3b, v72
	v_mul_f32_e32 v243, 0xbfb8aa3b, v73
	v_mul_f32_e32 v244, 0xbfb8aa3b, v74
	v_mul_f32_e32 v245, 0xbfb8aa3b, v75
	v_exp_f32_e32 v242, v242
	v_exp_f32_e32 v243, v243
	v_exp_f32_e32 v244, v244
	v_exp_f32_e32 v245, v245
	v_add_f32_e32 v242, 1.0, v242
	v_add_f32_e32 v243, 1.0, v243
	v_add_f32_e32 v244, 1.0, v244
	v_add_f32_e32 v245, 1.0, v245
	v_rcp_f32_e32 v242, v242
	v_rcp_f32_e32 v243, v243
	v_rcp_f32_e32 v244, v244
	v_rcp_f32_e32 v245, v245
	s_nop 0
	v_pk_mul_f32 v[72:73], v[72:73], v[242:243]
	v_pk_mul_f32 v[74:75], v[74:75], v[244:245]
	v_pk_mul_f32 v[72:73], v[88:89], v[72:73]
	v_pk_mul_f32 v[74:75], v[90:91], v[74:75]
	ds_write2_b32 v198, v72, v73 offset0:32 offset1:100
	ds_write2_b32 v198, v74, v75 offset0:168 offset1:236
	v_pk_mul_f32 v[76:77], v[76:77], v[226:227]
	v_pk_mul_f32 v[78:79], v[78:79], v[228:229]
	v_pk_mul_f32 v[92:93], v[92:93], v[226:227]
	v_pk_mul_f32 v[94:95], v[94:95], v[228:229]
	v_mul_f32_e32 v242, 0xbfb8aa3b, v76
	v_mul_f32_e32 v243, 0xbfb8aa3b, v77
	v_mul_f32_e32 v244, 0xbfb8aa3b, v78
	v_mul_f32_e32 v245, 0xbfb8aa3b, v79
	v_exp_f32_e32 v242, v242
	v_exp_f32_e32 v243, v243
	v_exp_f32_e32 v244, v244
	v_exp_f32_e32 v245, v245
	v_add_f32_e32 v242, 1.0, v242
	v_add_f32_e32 v243, 1.0, v243
	v_add_f32_e32 v244, 1.0, v244
	v_add_f32_e32 v245, 1.0, v245
	v_rcp_f32_e32 v242, v242
	v_rcp_f32_e32 v243, v243
	v_rcp_f32_e32 v244, v244
	v_rcp_f32_e32 v245, v245
	s_nop 0
	v_pk_mul_f32 v[76:77], v[76:77], v[242:243]
	v_pk_mul_f32 v[78:79], v[78:79], v[244:245]
	v_pk_mul_f32 v[76:77], v[92:93], v[76:77]
	v_pk_mul_f32 v[78:79], v[94:95], v[78:79]
	ds_write2_b32 v198, v76, v77 offset0:48 offset1:116
	ds_write2_b32 v198, v78, v79 offset0:184 offset1:252
	v_pk_mul_f32 v[96:97], v[96:97], v[230:231]
	v_pk_mul_f32 v[98:99], v[98:99], v[232:233]
	v_pk_mul_f32 v[112:113], v[112:113], v[230:231]
	v_pk_mul_f32 v[114:115], v[114:115], v[232:233]
	v_mul_f32_e32 v242, 0xbfb8aa3b, v96
	v_mul_f32_e32 v243, 0xbfb8aa3b, v97
	v_mul_f32_e32 v244, 0xbfb8aa3b, v98
	v_mul_f32_e32 v245, 0xbfb8aa3b, v99
	v_exp_f32_e32 v242, v242
	v_exp_f32_e32 v243, v243
	v_exp_f32_e32 v244, v244
	v_exp_f32_e32 v245, v245
	v_add_f32_e32 v242, 1.0, v242
	v_add_f32_e32 v243, 1.0, v243
	v_add_f32_e32 v244, 1.0, v244
	v_add_f32_e32 v245, 1.0, v245
	v_rcp_f32_e32 v242, v242
	v_rcp_f32_e32 v243, v243
	v_rcp_f32_e32 v244, v244
; DI void epi_slab(const GemmCfg c, const f32x16 (&acc)[4], float* sW, const float* rss, const size_t row0, const int g, const int lane,
;                  float* const g_h, u16* const g_hb, float* const g_out, const int final_out) {
;     ...
;   if (c.epi == EPI_SWIGLU) {
;     const int c4 = (ln_ & 15) * 4;
; #pragma unroll 2
;     for (int it = 0; it < 8; ++it) {
;       const int r = (ln_ >> 4) + 4 * it;
;       const float rs = rsqrtf(rss[r] * invK + 1e-6f);
;       f32x4 a = *(const f32x4*)(sW + r * 132 + c4);
;       f32x4 b = *(const f32x4*)(sW + r * 132 + 64 + c4);
;       float y[4];
; #pragma unroll
;       for (int e = 0; e < 4; ++e) { float av = a[e] * rs, bv = b[e] * rs; y[e] = av * __builtin_amdgcn_rcpf(1.f + __expf(-av)) * bv; }
;       *(u32x2*)(c.o16 + (row0 + r) * DFF + g * 64 + c4) = MK2(pack2(y[0], y[1]), pack2(y[2], y[3]));
;     }
	v_rcp_f32_e32 v245, v245
	s_nop 0
	v_pk_mul_f32 v[96:97], v[96:97], v[242:243]
	v_pk_mul_f32 v[98:99], v[98:99], v[244:245]
	v_pk_mul_f32 v[96:97], v[112:113], v[96:97]
	v_pk_mul_f32 v[98:99], v[114:115], v[98:99]
	ds_write2_b32 v199, v96, v97 offset0:0 offset1:68
	ds_write2_b32 v199, v98, v99 offset0:136 offset1:204
	v_pk_mul_f32 v[100:101], v[100:101], v[230:231]
	v_pk_mul_f32 v[102:103], v[102:103], v[232:233]
	v_pk_mul_f32 v[116:117], v[116:117], v[230:231]
	v_pk_mul_f32 v[118:119], v[118:119], v[232:233]
	v_mul_f32_e32 v242, 0xbfb8aa3b, v100
	v_mul_f32_e32 v243, 0xbfb8aa3b, v101
	v_mul_f32_e32 v244, 0xbfb8aa3b, v102
	v_mul_f32_e32 v245, 0xbfb8aa3b, v103
	v_exp_f32_e32 v242, v242
	v_exp_f32_e32 v243, v243
	v_exp_f32_e32 v244, v244
	v_exp_f32_e32 v245, v245
	v_add_f32_e32 v242, 1.0, v242
	v_add_f32_e32 v243, 1.0, v243
	v_add_f32_e32 v244, 1.0, v244
	v_add_f32_e32 v245, 1.0, v245
	v_rcp_f32_e32 v242, v242
	v_rcp_f32_e32 v243, v243
	v_rcp_f32_e32 v244, v244
	v_rcp_f32_e32 v245, v245
	s_nop 0
	v_pk_mul_f32 v[100:101], v[100:101], v[242:243]
	v_pk_mul_f32 v[102:103], v[102:103], v[244:245]
	v_pk_mul_f32 v[100:101], v[116:117], v[100:101]
	v_pk_mul_f32 v[102:103], v[118:119], v[102:103]
	ds_write2_b32 v199, v100, v101 offset0:16 offset1:84
	ds_write2_b32 v199, v102, v103 offset0:152 offset1:220
	v_pk_mul_f32 v[104:105], v[104:105], v[230:231]
	v_pk_mul_f32 v[106:107], v[106:107], v[232:233]
	v_pk_mul_f32 v[120:121], v[120:121], v[230:231]
	v_pk_mul_f32 v[122:123], v[122:123], v[232:233]
	v_mul_f32_e32 v242, 0xbfb8aa3b, v104
	v_mul_f32_e32 v243, 0xbfb8aa3b, v105
	v_mul_f32_e32 v244, 0xbfb8aa3b, v106
	v_mul_f32_e32 v245, 0xbfb8aa3b, v107
	v_exp_f32_e32 v242, v242
	v_exp_f32_e32 v243, v243
	v_exp_f32_e32 v244, v244
	v_exp_f32_e32 v245, v245
	v_add_f32_e32 v242, 1.0, v242
	v_add_f32_e32 v243, 1.0, v243
	v_add_f32_e32 v244, 1.0, v244
	v_add_f32_e32 v245, 1.0, v245
	v_rcp_f32_e32 v242, v242
	v_rcp_f32_e32 v243, v243
	v_rcp_f32_e32 v244, v244
	v_rcp_f32_e32 v245, v245
	s_nop 0
	v_pk_mul_f32 v[104:105], v[104:105], v[242:243]
	v_pk_mul_f32 v[106:107], v[106:107], v[244:245]
	v_pk_mul_f32 v[104:105], v[120:121], v[104:105]
	v_pk_mul_f32 v[106:107], v[122:123], v[106:107]
	ds_write2_b32 v199, v104, v105 offset0:32 offset1:100
	ds_write2_b32 v199, v106, v107 offset0:168 offset1:236
	v_pk_mul_f32 v[108:109], v[108:109], v[230:231]
	v_pk_mul_f32 v[110:111], v[110:111], v[232:233]
	v_pk_mul_f32 v[124:125], v[124:125], v[230:231]
	v_pk_mul_f32 v[126:127], v[126:127], v[232:233]
	v_mul_f32_e32 v242, 0xbfb8aa3b, v108
	v_mul_f32_e32 v243, 0xbfb8aa3b, v109
	v_mul_f32_e32 v244, 0xbfb8aa3b, v110
	v_mul_f32_e32 v245, 0xbfb8aa3b, v111
	v_exp_f32_e32 v242, v242
	v_exp_f32_e32 v243, v243
	v_exp_f32_e32 v244, v244
	v_exp_f32_e32 v245, v245
	v_add_f32_e32 v242, 1.0, v242
	v_add_f32_e32 v243, 1.0, v243
	v_add_f32_e32 v244, 1.0, v244
	v_add_f32_e32 v245, 1.0, v245
	v_rcp_f32_e32 v242, v242
	v_rcp_f32_e32 v243, v243
	v_rcp_f32_e32 v244, v244
	v_rcp_f32_e32 v245, v245
	s_nop 0
	v_pk_mul_f32 v[108:109], v[108:109], v[242:243]
	v_pk_mul_f32 v[110:111], v[110:111], v[244:245]
	v_pk_mul_f32 v[108:109], v[124:125], v[108:109]
	v_pk_mul_f32 v[110:111], v[126:127], v[110:111]
	ds_write2_b32 v199, v108, v109 offset0:48 offset1:116
	ds_write2_b32 v199, v110, v111 offset0:184 offset1:252
	s_waitcnt lgkmcnt(0)
	ds_read_b128 v[80:83], v200
	ds_read_b128 v[84:87], v200 offset:1088
	ds_read_b128 v[88:91], v200 offset:2176
	ds_read_b128 v[92:95], v200 offset:3264
	ds_read_b128 v[112:115], v200 offset:4352
	ds_read_b128 v[116:119], v200 offset:5440
	ds_read_b128 v[120:123], v200 offset:6528
	ds_read_b128 v[124:127], v200 offset:7616
	s_waitcnt lgkmcnt(7)
	v_lshl_add_u64 v[204:205], v[202:203], 0, s[8:9]
	v_cvt_pk_bf16_f32 v80, v80, v81
	v_cvt_pk_bf16_f32 v81, v82, v83
	s_add_u32 s8, s8, 0x5800
	s_addc_u32 s9, s9, 0
	global_store_dwordx2 v[204:205], v[80:81], off
	s_waitcnt lgkmcnt(6)
	v_lshl_add_u64 v[204:205], v[202:203], 0, s[8:9]
	v_cvt_pk_bf16_f32 v84, v84, v85
	v_cvt_pk_bf16_f32 v85, v86, v87
	s_add_u32 s8, s8, 0x5800
	s_addc_u32 s9, s9, 0
	global_store_dwordx2 v[204:205], v[84:85], off
	s_waitcnt lgkmcnt(5)
	v_lshl_add_u64 v[204:205], v[202:203], 0, s[8:9]
	v_cvt_pk_bf16_f32 v88, v88, v89
	v_cvt_pk_bf16_f32 v89, v90, v91
	s_add_u32 s8, s8, 0x5800
	s_addc_u32 s9, s9, 0
	global_store_dwordx2 v[204:205], v[88:89], off
	s_waitcnt lgkmcnt(4)
	v_lshl_add_u64 v[204:205], v[202:203], 0, s[8:9]
	v_cvt_pk_bf16_f32 v92, v92, v93
	v_cvt_pk_bf16_f32 v93, v94, v95
	s_add_u32 s8, s8, 0x5800
	s_addc_u32 s9, s9, 0
	global_store_dwordx2 v[204:205], v[92:93], off
	s_waitcnt lgkmcnt(3)
	v_lshl_add_u64 v[204:205], v[202:203], 0, s[8:9]
	v_cvt_pk_bf16_f32 v112, v112, v113
	v_cvt_pk_bf16_f32 v113, v114, v115
	s_add_u32 s8, s8, 0x5800
	s_addc_u32 s9, s9, 0
	global_store_dwordx2 v[204:205], v[112:113], off
	s_waitcnt lgkmcnt(2)
	v_lshl_add_u64 v[204:205], v[202:203], 0, s[8:9]
	v_cvt_pk_bf16_f32 v116, v116, v117
	v_cvt_pk_bf16_f32 v117, v118, v119
	s_add_u32 s8, s8, 0x5800
	s_addc_u32 s9, s9, 0
	global_store_dwordx2 v[204:205], v[116:117], off
	s_waitcnt lgkmcnt(1)
	v_lshl_add_u64 v[204:205], v[202:203], 0, s[8:9]
	v_cvt_pk_bf16_f32 v120, v120, v121
	v_cvt_pk_bf16_f32 v121, v122, v123
	s_add_u32 s8, s8, 0x5800
	s_addc_u32 s9, s9, 0
	global_store_dwordx2 v[204:205], v[120:121], off
	s_waitcnt lgkmcnt(0)
; DI void epi_slab(const GemmCfg c, const f32x16 (&acc)[4], float* sW, const float* rss, const size_t row0, const int g, const int lane,
;                  float* const g_h, u16* const g_hb, float* const g_out, const int final_out) {
;     ...
;   if (c.epi == EPI_SWIGLU) {
;     const int c4 = (ln_ & 15) * 4;
; #pragma unroll 2
;     for (int it = 0; it < 8; ++it) {
;       const int r = (ln_ >> 4) + 4 * it;
;       const float rs = rsqrtf(rss[r] * invK + 1e-6f);
;       f32x4 a = *(const f32x4*)(sW + r * 132 + c4);
;       f32x4 b = *(const f32x4*)(sW + r * 132 + 64 + c4);
;       float y[4];
; #pragma unroll
;       for (int e = 0; e < 4; ++e) { float av = a[e] * rs, bv = b[e] * rs; y[e] = av * __builtin_amdgcn_rcpf(1.f + __expf(-av)) * bv; }
;       *(u32x2*)(c.o16 + (row0 + r) * DFF + g * 64 + c4) = MK2(pack2(y[0], y[1]), pack2(y[2], y[3]));
;     }
	v_lshl_add_u64 v[204:205], v[202:203], 0, s[8:9]
	v_cvt_pk_bf16_f32 v124, v124, v125
	v_cvt_pk_bf16_f32 v125, v126, v127
	s_add_u32 s8, s8, 0x5800
	s_addc_u32 s9, s9, 0
	global_store_dwordx2 v[204:205], v[124:125], off
	v_pk_mul_f32 v[0:1], v[0:1], v[234:235]
	v_pk_mul_f32 v[2:3], v[2:3], v[236:237]
	v_pk_mul_f32 v[16:17], v[16:17], v[234:235]
	v_pk_mul_f32 v[18:19], v[18:19], v[236:237]
	v_mul_f32_e32 v242, 0xbfb8aa3b, v0
	v_mul_f32_e32 v243, 0xbfb8aa3b, v1
	v_mul_f32_e32 v244, 0xbfb8aa3b, v2
	v_mul_f32_e32 v245, 0xbfb8aa3b, v3
	v_exp_f32_e32 v242, v242
	v_exp_f32_e32 v243, v243
	v_exp_f32_e32 v244, v244
	v_exp_f32_e32 v245, v245
	v_add_f32_e32 v242, 1.0, v242
	v_add_f32_e32 v243, 1.0, v243
	v_add_f32_e32 v244, 1.0, v244
	v_add_f32_e32 v245, 1.0, v245
	v_rcp_f32_e32 v242, v242
	v_rcp_f32_e32 v243, v243
	v_rcp_f32_e32 v244, v244
	v_rcp_f32_e32 v245, v245
	s_nop 0
	v_pk_mul_f32 v[0:1], v[0:1], v[242:243]
	v_pk_mul_f32 v[2:3], v[2:3], v[244:245]
	v_pk_mul_f32 v[0:1], v[16:17], v[0:1]
	v_pk_mul_f32 v[2:3], v[18:19], v[2:3]
	ds_write2_b32 v198, v0, v1 offset0:0 offset1:68
	ds_write2_b32 v198, v2, v3 offset0:136 offset1:204
	v_pk_mul_f32 v[4:5], v[4:5], v[234:235]
	v_pk_mul_f32 v[6:7], v[6:7], v[236:237]
	v_pk_mul_f32 v[20:21], v[20:21], v[234:235]
	v_pk_mul_f32 v[22:23], v[22:23], v[236:237]
	v_mul_f32_e32 v242, 0xbfb8aa3b, v4
	v_mul_f32_e32 v243, 0xbfb8aa3b, v5
	v_mul_f32_e32 v244, 0xbfb8aa3b, v6
	v_mul_f32_e32 v245, 0xbfb8aa3b, v7
	v_exp_f32_e32 v242, v242
	v_exp_f32_e32 v243, v243
	v_exp_f32_e32 v244, v244
	v_exp_f32_e32 v245, v245
	v_add_f32_e32 v242, 1.0, v242
	v_add_f32_e32 v243, 1.0, v243
	v_add_f32_e32 v244, 1.0, v244
	v_add_f32_e32 v245, 1.0, v245
	v_rcp_f32_e32 v242, v242
	v_rcp_f32_e32 v243, v243
	v_rcp_f32_e32 v244, v244
	v_rcp_f32_e32 v245, v245
	s_nop 0
	v_pk_mul_f32 v[4:5], v[4:5], v[242:243]
	v_pk_mul_f32 v[6:7], v[6:7], v[244:245]
	v_pk_mul_f32 v[4:5], v[20:21], v[4:5]
	v_pk_mul_f32 v[6:7], v[22:23], v[6:7]
	ds_write2_b32 v198, v4, v5 offset0:16 offset1:84
	ds_write2_b32 v198, v6, v7 offset0:152 offset1:220
	v_pk_mul_f32 v[8:9], v[8:9], v[234:235]
	v_pk_mul_f32 v[10:11], v[10:11], v[236:237]
	v_pk_mul_f32 v[24:25], v[24:25], v[234:235]
	v_pk_mul_f32 v[26:27], v[26:27], v[236:237]
	v_mul_f32_e32 v242, 0xbfb8aa3b, v8
	v_mul_f32_e32 v243, 0xbfb8aa3b, v9
	v_mul_f32_e32 v244, 0xbfb8aa3b, v10
	v_mul_f32_e32 v245, 0xbfb8aa3b, v11
	v_exp_f32_e32 v242, v242
	v_exp_f32_e32 v243, v243
	v_exp_f32_e32 v244, v244
	v_exp_f32_e32 v245, v245
	v_add_f32_e32 v242, 1.0, v242
	v_add_f32_e32 v243, 1.0, v243
	v_add_f32_e32 v244, 1.0, v244
	v_add_f32_e32 v245, 1.0, v245
	v_rcp_f32_e32 v242, v242
	v_rcp_f32_e32 v243, v243
	v_rcp_f32_e32 v244, v244
	v_rcp_f32_e32 v245, v245
	s_nop 0
	v_pk_mul_f32 v[8:9], v[8:9], v[242:243]
	v_pk_mul_f32 v[10:11], v[10:11], v[244:245]
	v_pk_mul_f32 v[8:9], v[24:25], v[8:9]
	v_pk_mul_f32 v[10:11], v[26:27], v[10:11]
	ds_write2_b32 v198, v8, v9 offset0:32 offset1:100
	ds_write2_b32 v198, v10, v11 offset0:168 offset1:236
	v_pk_mul_f32 v[12:13], v[12:13], v[234:235]
	v_pk_mul_f32 v[14:15], v[14:15], v[236:237]
	v_pk_mul_f32 v[28:29], v[28:29], v[234:235]
	v_pk_mul_f32 v[30:31], v[30:31], v[236:237]
	v_mul_f32_e32 v242, 0xbfb8aa3b, v12
	v_mul_f32_e32 v243, 0xbfb8aa3b, v13
	v_mul_f32_e32 v244, 0xbfb8aa3b, v14
	v_mul_f32_e32 v245, 0xbfb8aa3b, v15
	v_exp_f32_e32 v242, v242
	v_exp_f32_e32 v243, v243
	v_exp_f32_e32 v244, v244
	v_exp_f32_e32 v245, v245
	v_add_f32_e32 v242, 1.0, v242
	v_add_f32_e32 v243, 1.0, v243
	v_add_f32_e32 v244, 1.0, v244
	v_add_f32_e32 v245, 1.0, v245
	v_rcp_f32_e32 v242, v242
	v_rcp_f32_e32 v243, v243
	v_rcp_f32_e32 v244, v244
	v_rcp_f32_e32 v245, v245
	s_nop 0
	v_pk_mul_f32 v[12:13], v[12:13], v[242:243]
	v_pk_mul_f32 v[14:15], v[14:15], v[244:245]
	v_pk_mul_f32 v[12:13], v[28:29], v[12:13]
	v_pk_mul_f32 v[14:15], v[30:31], v[14:15]
	ds_write2_b32 v198, v12, v13 offset0:48 offset1:116
	ds_write2_b32 v198, v14, v15 offset0:184 offset1:252
	v_pk_mul_f32 v[32:33], v[32:33], v[238:239]
	v_pk_mul_f32 v[34:35], v[34:35], v[240:241]
	v_pk_mul_f32 v[48:49], v[48:49], v[238:239]
	v_pk_mul_f32 v[50:51], v[50:51], v[240:241]
	v_mul_f32_e32 v242, 0xbfb8aa3b, v32
	v_mul_f32_e32 v243, 0xbfb8aa3b, v33
	v_mul_f32_e32 v244, 0xbfb8aa3b, v34
	v_mul_f32_e32 v245, 0xbfb8aa3b, v35
	v_exp_f32_e32 v242, v242
	v_exp_f32_e32 v243, v243
	v_exp_f32_e32 v244, v244
	v_exp_f32_e32 v245, v245
	v_add_f32_e32 v242, 1.0, v242
	v_add_f32_e32 v243, 1.0, v243
	v_add_f32_e32 v244, 1.0, v244
	v_add_f32_e32 v245, 1.0, v245
	v_rcp_f32_e32 v242, v242
	v_rcp_f32_e32 v243, v243
	v_rcp_f32_e32 v244, v244
	v_rcp_f32_e32 v245, v245
	s_nop 0
	v_pk_mul_f32 v[32:33], v[32:33], v[242:243]
	v_pk_mul_f32 v[34:35], v[34:35], v[244:245]
	v_pk_mul_f32 v[32:33], v[48:49], v[32:33]
	v_pk_mul_f32 v[34:35], v[50:51], v[34:35]
	ds_write2_b32 v199, v32, v33 offset0:0 offset1:68
	ds_write2_b32 v199, v34, v35 offset0:136 offset1:204
	v_pk_mul_f32 v[36:37], v[36:37], v[238:239]
	v_pk_mul_f32 v[38:39], v[38:39], v[240:241]
	v_pk_mul_f32 v[52:53], v[52:53], v[238:239]
	v_pk_mul_f32 v[54:55], v[54:55], v[240:241]
	v_mul_f32_e32 v242, 0xbfb8aa3b, v36
	v_mul_f32_e32 v243, 0xbfb8aa3b, v37
	v_mul_f32_e32 v244, 0xbfb8aa3b, v38
	v_mul_f32_e32 v245, 0xbfb8aa3b, v39
	v_exp_f32_e32 v242, v242
	v_exp_f32_e32 v243, v243
	v_exp_f32_e32 v244, v244
	v_exp_f32_e32 v245, v245
	v_add_f32_e32 v242, 1.0, v242
	v_add_f32_e32 v243, 1.0, v243
	v_add_f32_e32 v244, 1.0, v244
	v_add_f32_e32 v245, 1.0, v245
	v_rcp_f32_e32 v242, v242
	v_rcp_f32_e32 v243, v243
	v_rcp_f32_e32 v244, v244
	v_rcp_f32_e32 v245, v245
	s_nop 0
	v_pk_mul_f32 v[36:37], v[36:37], v[242:243]
	v_pk_mul_f32 v[38:39], v[38:39], v[244:245]
; DI void epi_slab(const GemmCfg c, const f32x16 (&acc)[4], float* sW, const float* rss, const size_t row0, const int g, const int lane,
;                  float* const g_h, u16* const g_hb, float* const g_out, const int final_out) {
;     ...
;   if (c.epi == EPI_SWIGLU) {
;     const int c4 = (ln_ & 15) * 4;
; #pragma unroll 2
;     for (int it = 0; it < 8; ++it) {
;       const int r = (ln_ >> 4) + 4 * it;
;       const float rs = rsqrtf(rss[r] * invK + 1e-6f);
;       f32x4 a = *(const f32x4*)(sW + r * 132 + c4);
;       f32x4 b = *(const f32x4*)(sW + r * 132 + 64 + c4);
;       float y[4];
; #pragma unroll
;       for (int e = 0; e < 4; ++e) { float av = a[e] * rs, bv = b[e] * rs; y[e] = av * __builtin_amdgcn_rcpf(1.f + __expf(-av)) * bv; }
;       *(u32x2*)(c.o16 + (row0 + r) * DFF + g * 64 + c4) = MK2(pack2(y[0], y[1]), pack2(y[2], y[3]));
;     }
	v_pk_mul_f32 v[36:37], v[52:53], v[36:37]
	v_pk_mul_f32 v[38:39], v[54:55], v[38:39]
	ds_write2_b32 v199, v36, v37 offset0:16 offset1:84
	ds_write2_b32 v199, v38, v39 offset0:152 offset1:220
	v_pk_mul_f32 v[40:41], v[40:41], v[238:239]
	v_pk_mul_f32 v[42:43], v[42:43], v[240:241]
	v_pk_mul_f32 v[56:57], v[56:57], v[238:239]
	v_pk_mul_f32 v[58:59], v[58:59], v[240:241]
	v_mul_f32_e32 v242, 0xbfb8aa3b, v40
	v_mul_f32_e32 v243, 0xbfb8aa3b, v41
	v_mul_f32_e32 v244, 0xbfb8aa3b, v42
	v_mul_f32_e32 v245, 0xbfb8aa3b, v43
	v_exp_f32_e32 v242, v242
	v_exp_f32_e32 v243, v243
	v_exp_f32_e32 v244, v244
	v_exp_f32_e32 v245, v245
	v_add_f32_e32 v242, 1.0, v242
	v_add_f32_e32 v243, 1.0, v243
	v_add_f32_e32 v244, 1.0, v244
	v_add_f32_e32 v245, 1.0, v245
	v_rcp_f32_e32 v242, v242
	v_rcp_f32_e32 v243, v243
	v_rcp_f32_e32 v244, v244
	v_rcp_f32_e32 v245, v245
	s_nop 0
	v_pk_mul_f32 v[40:41], v[40:41], v[242:243]
	v_pk_mul_f32 v[42:43], v[42:43], v[244:245]
	v_pk_mul_f32 v[40:41], v[56:57], v[40:41]
	v_pk_mul_f32 v[42:43], v[58:59], v[42:43]
	ds_write2_b32 v199, v40, v41 offset0:32 offset1:100
	ds_write2_b32 v199, v42, v43 offset0:168 offset1:236
	v_pk_mul_f32 v[44:45], v[44:45], v[238:239]
	v_pk_mul_f32 v[46:47], v[46:47], v[240:241]
	v_pk_mul_f32 v[60:61], v[60:61], v[238:239]
	v_pk_mul_f32 v[62:63], v[62:63], v[240:241]
	v_mul_f32_e32 v242, 0xbfb8aa3b, v44
	v_mul_f32_e32 v243, 0xbfb8aa3b, v45
	v_mul_f32_e32 v244, 0xbfb8aa3b, v46
	v_mul_f32_e32 v245, 0xbfb8aa3b, v47
	v_exp_f32_e32 v242, v242
	v_exp_f32_e32 v243, v243
	v_exp_f32_e32 v244, v244
	v_exp_f32_e32 v245, v245
	v_add_f32_e32 v242, 1.0, v242
	v_add_f32_e32 v243, 1.0, v243
	v_add_f32_e32 v244, 1.0, v244
	v_add_f32_e32 v245, 1.0, v245
	v_rcp_f32_e32 v242, v242
	v_rcp_f32_e32 v243, v243
	v_rcp_f32_e32 v244, v244
	v_rcp_f32_e32 v245, v245
	s_nop 0
	v_pk_mul_f32 v[44:45], v[44:45], v[242:243]
	v_pk_mul_f32 v[46:47], v[46:47], v[244:245]
	v_pk_mul_f32 v[44:45], v[60:61], v[44:45]
	v_pk_mul_f32 v[46:47], v[62:63], v[46:47]
	ds_write2_b32 v199, v44, v45 offset0:48 offset1:116
	ds_write2_b32 v199, v46, v47 offset0:184 offset1:252
	s_waitcnt lgkmcnt(0)
	ds_read_b128 v[16:19], v200
	ds_read_b128 v[20:23], v200 offset:1088
	ds_read_b128 v[24:27], v200 offset:2176
	ds_read_b128 v[28:31], v200 offset:3264
	ds_read_b128 v[48:51], v200 offset:4352
	ds_read_b128 v[52:55], v200 offset:5440
	ds_read_b128 v[56:59], v200 offset:6528
	ds_read_b128 v[60:63], v200 offset:7616
	s_waitcnt lgkmcnt(7)
	v_lshl_add_u64 v[204:205], v[202:203], 0, s[8:9]
	v_cvt_pk_bf16_f32 v16, v16, v17
	v_cvt_pk_bf16_f32 v17, v18, v19
	s_add_u32 s8, s8, 0x5800
	s_addc_u32 s9, s9, 0
	global_store_dwordx2 v[204:205], v[16:17], off
	s_waitcnt lgkmcnt(6)
	v_lshl_add_u64 v[204:205], v[202:203], 0, s[8:9]
	v_cvt_pk_bf16_f32 v20, v20, v21
	v_cvt_pk_bf16_f32 v21, v22, v23
	s_add_u32 s8, s8, 0x5800
	s_addc_u32 s9, s9, 0
	global_store_dwordx2 v[204:205], v[20:21], off
	s_waitcnt lgkmcnt(5)
	v_lshl_add_u64 v[204:205], v[202:203], 0, s[8:9]
	v_cvt_pk_bf16_f32 v24, v24, v25
	v_cvt_pk_bf16_f32 v25, v26, v27
	s_add_u32 s8, s8, 0x5800
	s_addc_u32 s9, s9, 0
	global_store_dwordx2 v[204:205], v[24:25], off
	s_waitcnt lgkmcnt(4)
	v_lshl_add_u64 v[204:205], v[202:203], 0, s[8:9]
	v_cvt_pk_bf16_f32 v28, v28, v29
	v_cvt_pk_bf16_f32 v29, v30, v31
	s_add_u32 s8, s8, 0x5800
	s_addc_u32 s9, s9, 0
	global_store_dwordx2 v[204:205], v[28:29], off
	s_waitcnt lgkmcnt(3)
	v_lshl_add_u64 v[204:205], v[202:203], 0, s[8:9]
	v_cvt_pk_bf16_f32 v48, v48, v49
	v_cvt_pk_bf16_f32 v49, v50, v51
	s_add_u32 s8, s8, 0x5800
	s_addc_u32 s9, s9, 0
	global_store_dwordx2 v[204:205], v[48:49], off
	s_waitcnt lgkmcnt(2)
	v_lshl_add_u64 v[204:205], v[202:203], 0, s[8:9]
	v_cvt_pk_bf16_f32 v52, v52, v53
	v_cvt_pk_bf16_f32 v53, v54, v55
	s_add_u32 s8, s8, 0x5800
	s_addc_u32 s9, s9, 0
	global_store_dwordx2 v[204:205], v[52:53], off
	s_waitcnt lgkmcnt(1)
	v_lshl_add_u64 v[204:205], v[202:203], 0, s[8:9]
	v_cvt_pk_bf16_f32 v56, v56, v57
	v_cvt_pk_bf16_f32 v57, v58, v59
	s_add_u32 s8, s8, 0x5800
	s_addc_u32 s9, s9, 0
	global_store_dwordx2 v[204:205], v[56:57], off
	s_waitcnt lgkmcnt(0)
	v_lshl_add_u64 v[204:205], v[202:203], 0, s[8:9]
	v_cvt_pk_bf16_f32 v60, v60, v61
	v_cvt_pk_bf16_f32 v61, v62, v63
	s_add_u32 s8, s8, 0x5800
	s_addc_u32 s9, s9, 0
	global_store_dwordx2 v[204:205], v[60:61], off
	s_branch .LBB0_108
; DI float shx(float v, int mask, int lane) { return __int_as_float(__builtin_amdgcn_ds_bpermute((lane ^ mask) << 2, __float_as_int(v))); }
; DI void epi_slab(const GemmCfg c, const f32x16 (&acc)[4], float* sW, const float* rss, const size_t row0, const int g, const int lane,
;                  float* const g_h, u16* const g_hb, float* const g_out, const int final_out) {
;     ...
;   } else {
;     const int c4 = l31 * 4;
;     const int col = g * 128 + c4;
; #pragma unroll 2
;     for (int it = 0; it < 16; ++it) {
;       const int r = hh + 2 * it;
;       const size_t row = row0 + r;
;       f32x4 v = *(const f32x4*)(sW + r * 132 + c4);
;       const float rs = c.use_rs ? rsqrtf(rss[r] * invK + 1e-6f) : 1.f;
;       if (c.epi == EPI_QKV) {
;         f32x4 x = v * rs;
;         float s = x[0] * x[0] + x[1] * x[1] + x[2] * x[2] + x[3] * x[3];
;         s += shx(s, 1, ln_); s += shx(s, 2, ln_); s += shx(s, 4, ln_); s += shx(s, 8, ln_);
;         if (g < c.nk_end) {
;           const float r2 = rsqrtf(s * (1.f / 64.f) + 1e-6f) * (g < 8 ? 0.125f * LOG2E : 1.f);
;           f32x4 gn = *(const f32x4*)(c.gain + (g < 8 ? 0 : 64) + (c4 & 63));
;           x = x * gn * r2;
;         }
;         *(u32x2*)(c.o16 + row * c.ldo + col) = MK2(pack2(x[0], x[1]), pack2(x[2], x[3]));
.Lqkv2:
	v_and_b32_e32 v222, 15, v185
	v_lshrrev_b32_e32 v223, 4, v185
	s_lshl_b32 s4, s86, 2
	s_add_i32 s4, s4, 0x24000
	v_lshl_add_u32 v224, v223, 4, s4
	ds_read_b128 v[226:229], v224
	ds_read_b128 v[230:233], v224 offset:64
	ds_read_b128 v[234:237], v224 offset:128
	ds_read_b128 v[238:241], v224 offset:192
	v_lshlrev_b32_e32 v206, 2, v222
	global_load_dword v132, v206, s[58:59]
	global_load_dword v134, v206, s[58:59] offset:64
	global_load_dword v136, v206, s[58:59] offset:128
	global_load_dword v138, v206, s[58:59] offset:192
	v_mul_u32_u24_e32 v198, 0x840, v223
	v_lshl_add_u32 v198, v222, 2, v198
	v_add_u32_e32 v198, s53, v198
	v_add_u32_e32 v199, 0x420, v198
	v_add_u32_e32 v200, 0x2100, v198
	v_add_u32_e32 v201, 0x2520, v198
	v_lshrrev_b32_e32 v202, 5, v185
	v_and_b32_e32 v206, 31, v185
	v_mul_u32_u24_e32 v204, 0x210, v202
	v_lshl_add_u32 v204, v206, 4, v204
	v_add_u32_e32 v250, s53, v204
	v_add_u32_e32 v204, s6, v202
	v_mul_lo_u32 v204, v204, s92
	v_lshl_add_u32 v206, v206, 2, s64
	v_lshl_add_u32 v204, v206, 1, v204
	v_mov_b32_e32 v205, 0
	v_lshl_add_u64 v[204:205], v[204:205], 0, s[56:57]
	v_mov_b32_e32 v202, v250
	v_mov_b32_e32 v250, 0x3c800000
	s_lshl_b32 s4, s92, 1
	s_mov_b64 s[8:9], 0
	s_waitcnt lgkmcnt(0)
	v_fmaak_f32 v226, v191, v226, 0x358637bd
	v_fmaak_f32 v227, v191, v227, 0x358637bd
	v_rsq_f32_e32 v226, v226
	v_rsq_f32_e32 v227, v227
	s_nop 0
	v_fmaak_f32 v228, v191, v228, 0x358637bd
	v_fmaak_f32 v229, v191, v229, 0x358637bd
	v_rsq_f32_e32 v228, v228
	v_rsq_f32_e32 v229, v229
	s_nop 0
	v_fmaak_f32 v230, v191, v230, 0x358637bd
	v_fmaak_f32 v231, v191, v231, 0x358637bd
	v_rsq_f32_e32 v230, v230
	v_rsq_f32_e32 v231, v231
	s_nop 0
	v_fmaak_f32 v232, v191, v232, 0x358637bd
	v_fmaak_f32 v233, v191, v233, 0x358637bd
	v_rsq_f32_e32 v232, v232
	v_rsq_f32_e32 v233, v233
	s_nop 0
	v_fmaak_f32 v234, v191, v234, 0x358637bd
	v_fmaak_f32 v235, v191, v235, 0x358637bd
	v_rsq_f32_e32 v234, v234
	v_rsq_f32_e32 v235, v235
	s_nop 0
	v_fmaak_f32 v236, v191, v236, 0x358637bd
	v_fmaak_f32 v237, v191, v237, 0x358637bd
	v_rsq_f32_e32 v236, v236
	v_rsq_f32_e32 v237, v237
	s_nop 0
	v_fmaak_f32 v238, v191, v238, 0x358637bd
	v_fmaak_f32 v239, v191, v239, 0x358637bd
	v_rsq_f32_e32 v238, v238
	v_rsq_f32_e32 v239, v239
	s_nop 0
	v_fmaak_f32 v240, v191, v240, 0x358637bd
	v_fmaak_f32 v241, v191, v241, 0x358637bd
	v_rsq_f32_e32 v240, v240
	v_rsq_f32_e32 v241, v241
	s_nop 0
	s_waitcnt vmcnt(0)
	v_pk_mul_f32 v[64:65], v[64:65], v[226:227]
	v_pk_mul_f32 v[66:67], v[66:67], v[228:229]
	v_pk_mul_f32 v[68:69], v[68:69], v[226:227]
	v_pk_mul_f32 v[70:71], v[70:71], v[228:229]
	v_pk_mul_f32 v[72:73], v[72:73], v[226:227]
	v_pk_mul_f32 v[74:75], v[74:75], v[228:229]
	v_pk_mul_f32 v[76:77], v[76:77], v[226:227]
	v_pk_mul_f32 v[78:79], v[78:79], v[228:229]
	v_pk_mul_f32 v[80:81], v[80:81], v[226:227]
	v_pk_mul_f32 v[82:83], v[82:83], v[228:229]
	v_pk_mul_f32 v[84:85], v[84:85], v[226:227]
	v_pk_mul_f32 v[86:87], v[86:87], v[228:229]
	v_pk_mul_f32 v[88:89], v[88:89], v[226:227]
	v_pk_mul_f32 v[90:91], v[90:91], v[228:229]
	v_pk_mul_f32 v[92:93], v[92:93], v[226:227]
	v_pk_mul_f32 v[94:95], v[94:95], v[228:229]
	s_and_b64 vcc, exec, s[72:73]
	s_cbranch_vccz .Lqkv2_plain0
	v_mul_f32_e32 v246, v64, v64
	v_mul_f32_e32 v247, v65, v65
	v_mul_f32_e32 v248, v66, v66
	v_mul_f32_e32 v249, v67, v67
	v_fmac_f32_e32 v246, v68, v68
	v_fmac_f32_e32 v247, v69, v69
	v_fmac_f32_e32 v248, v70, v70
	v_fmac_f32_e32 v249, v71, v71
	v_fmac_f32_e32 v246, v72, v72
	v_fmac_f32_e32 v247, v73, v73
	v_fmac_f32_e32 v248, v74, v74
	v_fmac_f32_e32 v249, v75, v75
	v_fmac_f32_e32 v246, v76, v76
	v_fmac_f32_e32 v247, v77, v77
	v_fmac_f32_e32 v248, v78, v78
	v_fmac_f32_e32 v249, v79, v79
	v_add_f32_dpp v246, v246, v246 quad_perm:[1,0,3,2] row_mask:0xf bank_mask:0xf
	v_add_f32_dpp v247, v247, v247 quad_perm:[1,0,3,2] row_mask:0xf bank_mask:0xf
	v_add_f32_dpp v248, v248, v248 quad_perm:[1,0,3,2] row_mask:0xf bank_mask:0xf
	v_add_f32_dpp v249, v249, v249 quad_perm:[1,0,3,2] row_mask:0xf bank_mask:0xf
	v_add_f32_dpp v246, v246, v246 quad_perm:[2,3,0,1] row_mask:0xf bank_mask:0xf
	v_add_f32_dpp v247, v247, v247 quad_perm:[2,3,0,1] row_mask:0xf bank_mask:0xf
	v_add_f32_dpp v248, v248, v248 quad_perm:[2,3,0,1] row_mask:0xf bank_mask:0xf
	v_add_f32_dpp v249, v249, v249 quad_perm:[2,3,0,1] row_mask:0xf bank_mask:0xf
	v_add_f32_dpp v246, v246, v246 row_half_mirror row_mask:0xf bank_mask:0xf
	v_add_f32_dpp v247, v247, v247 row_half_mirror row_mask:0xf bank_mask:0xf
	v_add_f32_dpp v248, v248, v248 row_half_mirror row_mask:0xf bank_mask:0xf
	v_add_f32_dpp v249, v249, v249 row_half_mirror row_mask:0xf bank_mask:0xf
	v_add_f32_dpp v246, v246, v246 row_mirror row_mask:0xf bank_mask:0xf
	v_add_f32_dpp v247, v247, v247 row_mirror row_mask:0xf bank_mask:0xf
	v_add_f32_dpp v248, v248, v248 row_mirror row_mask:0xf bank_mask:0xf
	v_add_f32_dpp v249, v249, v249 row_mirror row_mask:0xf bank_mask:0xf
	v_fmaak_f32 v246, v250, v246, 0x358637bd
	v_fmaak_f32 v247, v250, v247, 0x358637bd
	v_rsq_f32_e32 v246, v246
	v_rsq_f32_e32 v247, v247
	s_nop 0
	v_mul_f32_e32 v246, v130, v246
	v_mul_f32_e32 v247, v130, v247
	v_fmaak_f32 v248, v250, v248, 0x358637bd
	v_fmaak_f32 v249, v250, v249, 0x358637bd
	v_rsq_f32_e32 v248, v248
	v_rsq_f32_e32 v249, v249
	s_nop 0
	v_mul_f32_e32 v248, v130, v248
	v_mul_f32_e32 v249, v130, v249
	v_pk_mul_f32 v[64:65], v[64:65], v[246:247]
	v_pk_mul_f32 v[66:67], v[66:67], v[248:249]
	v_pk_mul_f32 v[64:65], v[64:65], v[132:133] op_sel_hi:[1,0]
	v_pk_mul_f32 v[66:67], v[66:67], v[132:133] op_sel_hi:[1,0]
	v_pk_mul_f32 v[68:69], v[68:69], v[246:247]
	v_pk_mul_f32 v[70:71], v[70:71], v[248:249]
; DI float shx(float v, int mask, int lane) { return __int_as_float(__builtin_amdgcn_ds_bpermute((lane ^ mask) << 2, __float_as_int(v))); }
; DI void epi_slab(const GemmCfg c, const f32x16 (&acc)[4], float* sW, const float* rss, const size_t row0, const int g, const int lane,
;                  float* const g_h, u16* const g_hb, float* const g_out, const int final_out) {
;     ...
;   } else {
;     const int c4 = l31 * 4;
;     const int col = g * 128 + c4;
; #pragma unroll 2
;     for (int it = 0; it < 16; ++it) {
;       const int r = hh + 2 * it;
;       const size_t row = row0 + r;
;       f32x4 v = *(const f32x4*)(sW + r * 132 + c4);
;       const float rs = c.use_rs ? rsqrtf(rss[r] * invK + 1e-6f) : 1.f;
;       if (c.epi == EPI_QKV) {
;         f32x4 x = v * rs;
;         float s = x[0] * x[0] + x[1] * x[1] + x[2] * x[2] + x[3] * x[3];
;         s += shx(s, 1, ln_); s += shx(s, 2, ln_); s += shx(s, 4, ln_); s += shx(s, 8, ln_);
;         if (g < c.nk_end) {
;           const float r2 = rsqrtf(s * (1.f / 64.f) + 1e-6f) * (g < 8 ? 0.125f * LOG2E : 1.f);
;           f32x4 gn = *(const f32x4*)(c.gain + (g < 8 ? 0 : 64) + (c4 & 63));
;           x = x * gn * r2;
;         }
;         *(u32x2*)(c.o16 + row * c.ldo + col) = MK2(pack2(x[0], x[1]), pack2(x[2], x[3]));
	v_pk_mul_f32 v[68:69], v[68:69], v[134:135] op_sel_hi:[1,0]
	v_pk_mul_f32 v[70:71], v[70:71], v[134:135] op_sel_hi:[1,0]
	v_pk_mul_f32 v[72:73], v[72:73], v[246:247]
	v_pk_mul_f32 v[74:75], v[74:75], v[248:249]
	v_pk_mul_f32 v[72:73], v[72:73], v[136:137] op_sel_hi:[1,0]
	v_pk_mul_f32 v[74:75], v[74:75], v[136:137] op_sel_hi:[1,0]
	v_pk_mul_f32 v[76:77], v[76:77], v[246:247]
	v_pk_mul_f32 v[78:79], v[78:79], v[248:249]
	v_pk_mul_f32 v[76:77], v[76:77], v[138:139] op_sel_hi:[1,0]
	v_pk_mul_f32 v[78:79], v[78:79], v[138:139] op_sel_hi:[1,0]
	v_mul_f32_e32 v246, v80, v80
	v_mul_f32_e32 v247, v81, v81
	v_mul_f32_e32 v248, v82, v82
	v_mul_f32_e32 v249, v83, v83
	v_fmac_f32_e32 v246, v84, v84
	v_fmac_f32_e32 v247, v85, v85
	v_fmac_f32_e32 v248, v86, v86
	v_fmac_f32_e32 v249, v87, v87
	v_fmac_f32_e32 v246, v88, v88
	v_fmac_f32_e32 v247, v89, v89
	v_fmac_f32_e32 v248, v90, v90
	v_fmac_f32_e32 v249, v91, v91
	v_fmac_f32_e32 v246, v92, v92
	v_fmac_f32_e32 v247, v93, v93
	v_fmac_f32_e32 v248, v94, v94
	v_fmac_f32_e32 v249, v95, v95
	v_add_f32_dpp v246, v246, v246 quad_perm:[1,0,3,2] row_mask:0xf bank_mask:0xf
	v_add_f32_dpp v247, v247, v247 quad_perm:[1,0,3,2] row_mask:0xf bank_mask:0xf
	v_add_f32_dpp v248, v248, v248 quad_perm:[1,0,3,2] row_mask:0xf bank_mask:0xf
	v_add_f32_dpp v249, v249, v249 quad_perm:[1,0,3,2] row_mask:0xf bank_mask:0xf
	v_add_f32_dpp v246, v246, v246 quad_perm:[2,3,0,1] row_mask:0xf bank_mask:0xf
	v_add_f32_dpp v247, v247, v247 quad_perm:[2,3,0,1] row_mask:0xf bank_mask:0xf
	v_add_f32_dpp v248, v248, v248 quad_perm:[2,3,0,1] row_mask:0xf bank_mask:0xf
	v_add_f32_dpp v249, v249, v249 quad_perm:[2,3,0,1] row_mask:0xf bank_mask:0xf
	v_add_f32_dpp v246, v246, v246 row_half_mirror row_mask:0xf bank_mask:0xf
	v_add_f32_dpp v247, v247, v247 row_half_mirror row_mask:0xf bank_mask:0xf
	v_add_f32_dpp v248, v248, v248 row_half_mirror row_mask:0xf bank_mask:0xf
	v_add_f32_dpp v249, v249, v249 row_half_mirror row_mask:0xf bank_mask:0xf
	v_add_f32_dpp v246, v246, v246 row_mirror row_mask:0xf bank_mask:0xf
	v_add_f32_dpp v247, v247, v247 row_mirror row_mask:0xf bank_mask:0xf
	v_add_f32_dpp v248, v248, v248 row_mirror row_mask:0xf bank_mask:0xf
	v_add_f32_dpp v249, v249, v249 row_mirror row_mask:0xf bank_mask:0xf
	v_fmaak_f32 v246, v250, v246, 0x358637bd
	v_fmaak_f32 v247, v250, v247, 0x358637bd
	v_rsq_f32_e32 v246, v246
	v_rsq_f32_e32 v247, v247
	s_nop 0
	v_mul_f32_e32 v246, v130, v246
	v_mul_f32_e32 v247, v130, v247
	v_fmaak_f32 v248, v250, v248, 0x358637bd
	v_fmaak_f32 v249, v250, v249, 0x358637bd
	v_rsq_f32_e32 v248, v248
	v_rsq_f32_e32 v249, v249
	s_nop 0
	v_mul_f32_e32 v248, v130, v248
	v_mul_f32_e32 v249, v130, v249
	v_pk_mul_f32 v[80:81], v[80:81], v[246:247]
	v_pk_mul_f32 v[82:83], v[82:83], v[248:249]
	v_pk_mul_f32 v[80:81], v[80:81], v[132:133] op_sel_hi:[1,0]
	v_pk_mul_f32 v[82:83], v[82:83], v[132:133] op_sel_hi:[1,0]
	v_pk_mul_f32 v[84:85], v[84:85], v[246:247]
	v_pk_mul_f32 v[86:87], v[86:87], v[248:249]
	v_pk_mul_f32 v[84:85], v[84:85], v[134:135] op_sel_hi:[1,0]
	v_pk_mul_f32 v[86:87], v[86:87], v[134:135] op_sel_hi:[1,0]
	v_pk_mul_f32 v[88:89], v[88:89], v[246:247]
	v_pk_mul_f32 v[90:91], v[90:91], v[248:249]
	v_pk_mul_f32 v[88:89], v[88:89], v[136:137] op_sel_hi:[1,0]
	v_pk_mul_f32 v[90:91], v[90:91], v[136:137] op_sel_hi:[1,0]
	v_pk_mul_f32 v[92:93], v[92:93], v[246:247]
	v_pk_mul_f32 v[94:95], v[94:95], v[248:249]
	v_pk_mul_f32 v[92:93], v[92:93], v[138:139] op_sel_hi:[1,0]
	v_pk_mul_f32 v[94:95], v[94:95], v[138:139] op_sel_hi:[1,0]
.Lqkv2_plain0:
	ds_write2_b32 v198, v64, v65 offset0:0 offset1:132
	ds_write2_b32 v199, v66, v67 offset0:0 offset1:132
	ds_write2_b32 v198, v68, v69 offset0:16 offset1:148
	ds_write2_b32 v199, v70, v71 offset0:16 offset1:148
	ds_write2_b32 v198, v72, v73 offset0:32 offset1:164
	ds_write2_b32 v199, v74, v75 offset0:32 offset1:164
	ds_write2_b32 v198, v76, v77 offset0:48 offset1:180
	ds_write2_b32 v199, v78, v79 offset0:48 offset1:180
	ds_write2_b32 v198, v80, v81 offset0:64 offset1:196
	ds_write2_b32 v199, v82, v83 offset0:64 offset1:196
	ds_write2_b32 v198, v84, v85 offset0:80 offset1:212
	ds_write2_b32 v199, v86, v87 offset0:80 offset1:212
	ds_write2_b32 v198, v88, v89 offset0:96 offset1:228
	ds_write2_b32 v199, v90, v91 offset0:96 offset1:228
	ds_write2_b32 v198, v92, v93 offset0:112 offset1:244
	ds_write2_b32 v199, v94, v95 offset0:112 offset1:244
	v_pk_mul_f32 v[96:97], v[96:97], v[230:231]
	v_pk_mul_f32 v[98:99], v[98:99], v[232:233]
	v_pk_mul_f32 v[100:101], v[100:101], v[230:231]
	v_pk_mul_f32 v[102:103], v[102:103], v[232:233]
	v_pk_mul_f32 v[104:105], v[104:105], v[230:231]
	v_pk_mul_f32 v[106:107], v[106:107], v[232:233]
	v_pk_mul_f32 v[108:109], v[108:109], v[230:231]
	v_pk_mul_f32 v[110:111], v[110:111], v[232:233]
	v_pk_mul_f32 v[112:113], v[112:113], v[230:231]
	v_pk_mul_f32 v[114:115], v[114:115], v[232:233]
	v_pk_mul_f32 v[116:117], v[116:117], v[230:231]
	v_pk_mul_f32 v[118:119], v[118:119], v[232:233]
	v_pk_mul_f32 v[120:121], v[120:121], v[230:231]
	v_pk_mul_f32 v[122:123], v[122:123], v[232:233]
	v_pk_mul_f32 v[124:125], v[124:125], v[230:231]
	v_pk_mul_f32 v[126:127], v[126:127], v[232:233]
	s_and_b64 vcc, exec, s[72:73]
	s_cbranch_vccz .Lqkv2_plain1
; DI float shx(float v, int mask, int lane) { return __int_as_float(__builtin_amdgcn_ds_bpermute((lane ^ mask) << 2, __float_as_int(v))); }
; DI void epi_slab(const GemmCfg c, const f32x16 (&acc)[4], float* sW, const float* rss, const size_t row0, const int g, const int lane,
;                  float* const g_h, u16* const g_hb, float* const g_out, const int final_out) {
;     ...
;   } else {
;     const int c4 = l31 * 4;
;     const int col = g * 128 + c4;
; #pragma unroll 2
;     for (int it = 0; it < 16; ++it) {
;       const int r = hh + 2 * it;
;       const size_t row = row0 + r;
;       f32x4 v = *(const f32x4*)(sW + r * 132 + c4);
;       const float rs = c.use_rs ? rsqrtf(rss[r] * invK + 1e-6f) : 1.f;
;       if (c.epi == EPI_QKV) {
;         f32x4 x = v * rs;
;         float s = x[0] * x[0] + x[1] * x[1] + x[2] * x[2] + x[3] * x[3];
;         s += shx(s, 1, ln_); s += shx(s, 2, ln_); s += shx(s, 4, ln_); s += shx(s, 8, ln_);
;         if (g < c.nk_end) {
;           const float r2 = rsqrtf(s * (1.f / 64.f) + 1e-6f) * (g < 8 ? 0.125f * LOG2E : 1.f);
;           f32x4 gn = *(const f32x4*)(c.gain + (g < 8 ? 0 : 64) + (c4 & 63));
;           x = x * gn * r2;
;         }
;         *(u32x2*)(c.o16 + row * c.ldo + col) = MK2(pack2(x[0], x[1]), pack2(x[2], x[3]));
	v_mul_f32_e32 v246, v96, v96
	v_mul_f32_e32 v247, v97, v97
	v_mul_f32_e32 v248, v98, v98
	v_mul_f32_e32 v249, v99, v99
	v_fmac_f32_e32 v246, v100, v100
	v_fmac_f32_e32 v247, v101, v101
	v_fmac_f32_e32 v248, v102, v102
	v_fmac_f32_e32 v249, v103, v103
	v_fmac_f32_e32 v246, v104, v104
	v_fmac_f32_e32 v247, v105, v105
	v_fmac_f32_e32 v248, v106, v106
	v_fmac_f32_e32 v249, v107, v107
	v_fmac_f32_e32 v246, v108, v108
	v_fmac_f32_e32 v247, v109, v109
	v_fmac_f32_e32 v248, v110, v110
	v_fmac_f32_e32 v249, v111, v111
	v_add_f32_dpp v246, v246, v246 quad_perm:[1,0,3,2] row_mask:0xf bank_mask:0xf
	v_add_f32_dpp v247, v247, v247 quad_perm:[1,0,3,2] row_mask:0xf bank_mask:0xf
	v_add_f32_dpp v248, v248, v248 quad_perm:[1,0,3,2] row_mask:0xf bank_mask:0xf
	v_add_f32_dpp v249, v249, v249 quad_perm:[1,0,3,2] row_mask:0xf bank_mask:0xf
	v_add_f32_dpp v246, v246, v246 quad_perm:[2,3,0,1] row_mask:0xf bank_mask:0xf
	v_add_f32_dpp v247, v247, v247 quad_perm:[2,3,0,1] row_mask:0xf bank_mask:0xf
	v_add_f32_dpp v248, v248, v248 quad_perm:[2,3,0,1] row_mask:0xf bank_mask:0xf
	v_add_f32_dpp v249, v249, v249 quad_perm:[2,3,0,1] row_mask:0xf bank_mask:0xf
	v_add_f32_dpp v246, v246, v246 row_half_mirror row_mask:0xf bank_mask:0xf
	v_add_f32_dpp v247, v247, v247 row_half_mirror row_mask:0xf bank_mask:0xf
	v_add_f32_dpp v248, v248, v248 row_half_mirror row_mask:0xf bank_mask:0xf
	v_add_f32_dpp v249, v249, v249 row_half_mirror row_mask:0xf bank_mask:0xf
	v_add_f32_dpp v246, v246, v246 row_mirror row_mask:0xf bank_mask:0xf
	v_add_f32_dpp v247, v247, v247 row_mirror row_mask:0xf bank_mask:0xf
	v_add_f32_dpp v248, v248, v248 row_mirror row_mask:0xf bank_mask:0xf
	v_add_f32_dpp v249, v249, v249 row_mirror row_mask:0xf bank_mask:0xf
	v_fmaak_f32 v246, v250, v246, 0x358637bd
	v_fmaak_f32 v247, v250, v247, 0x358637bd
	v_rsq_f32_e32 v246, v246
	v_rsq_f32_e32 v247, v247
	s_nop 0
	v_mul_f32_e32 v246, v130, v246
	v_mul_f32_e32 v247, v130, v247
	v_fmaak_f32 v248, v250, v248, 0x358637bd
	v_fmaak_f32 v249, v250, v249, 0x358637bd
	v_rsq_f32_e32 v248, v248
	v_rsq_f32_e32 v249, v249
	s_nop 0
	v_mul_f32_e32 v248, v130, v248
	v_mul_f32_e32 v249, v130, v249
	v_pk_mul_f32 v[96:97], v[96:97], v[246:247]
	v_pk_mul_f32 v[98:99], v[98:99], v[248:249]
	v_pk_mul_f32 v[96:97], v[96:97], v[132:133] op_sel_hi:[1,0]
	v_pk_mul_f32 v[98:99], v[98:99], v[132:133] op_sel_hi:[1,0]
	v_pk_mul_f32 v[100:101], v[100:101], v[246:247]
	v_pk_mul_f32 v[102:103], v[102:103], v[248:249]
	v_pk_mul_f32 v[100:101], v[100:101], v[134:135] op_sel_hi:[1,0]
	v_pk_mul_f32 v[102:103], v[102:103], v[134:135] op_sel_hi:[1,0]
	v_pk_mul_f32 v[104:105], v[104:105], v[246:247]
	v_pk_mul_f32 v[106:107], v[106:107], v[248:249]
	v_pk_mul_f32 v[104:105], v[104:105], v[136:137] op_sel_hi:[1,0]
	v_pk_mul_f32 v[106:107], v[106:107], v[136:137] op_sel_hi:[1,0]
	v_pk_mul_f32 v[108:109], v[108:109], v[246:247]
	v_pk_mul_f32 v[110:111], v[110:111], v[248:249]
	v_pk_mul_f32 v[108:109], v[108:109], v[138:139] op_sel_hi:[1,0]
	v_pk_mul_f32 v[110:111], v[110:111], v[138:139] op_sel_hi:[1,0]
	v_mul_f32_e32 v246, v112, v112
	v_mul_f32_e32 v247, v113, v113
	v_mul_f32_e32 v248, v114, v114
	v_mul_f32_e32 v249, v115, v115
	v_fmac_f32_e32 v246, v116, v116
	v_fmac_f32_e32 v247, v117, v117
	v_fmac_f32_e32 v248, v118, v118
	v_fmac_f32_e32 v249, v119, v119
	v_fmac_f32_e32 v246, v120, v120
	v_fmac_f32_e32 v247, v121, v121
	v_fmac_f32_e32 v248, v122, v122
	v_fmac_f32_e32 v249, v123, v123
	v_fmac_f32_e32 v246, v124, v124
	v_fmac_f32_e32 v247, v125, v125
	v_fmac_f32_e32 v248, v126, v126
	v_fmac_f32_e32 v249, v127, v127
	v_add_f32_dpp v246, v246, v246 quad_perm:[1,0,3,2] row_mask:0xf bank_mask:0xf
	v_add_f32_dpp v247, v247, v247 quad_perm:[1,0,3,2] row_mask:0xf bank_mask:0xf
	v_add_f32_dpp v248, v248, v248 quad_perm:[1,0,3,2] row_mask:0xf bank_mask:0xf
	v_add_f32_dpp v249, v249, v249 quad_perm:[1,0,3,2] row_mask:0xf bank_mask:0xf
	v_add_f32_dpp v246, v246, v246 quad_perm:[2,3,0,1] row_mask:0xf bank_mask:0xf
	v_add_f32_dpp v247, v247, v247 quad_perm:[2,3,0,1] row_mask:0xf bank_mask:0xf
	v_add_f32_dpp v248, v248, v248 quad_perm:[2,3,0,1] row_mask:0xf bank_mask:0xf
	v_add_f32_dpp v249, v249, v249 quad_perm:[2,3,0,1] row_mask:0xf bank_mask:0xf
	v_add_f32_dpp v246, v246, v246 row_half_mirror row_mask:0xf bank_mask:0xf
	v_add_f32_dpp v247, v247, v247 row_half_mirror row_mask:0xf bank_mask:0xf
	v_add_f32_dpp v248, v248, v248 row_half_mirror row_mask:0xf bank_mask:0xf
	v_add_f32_dpp v249, v249, v249 row_half_mirror row_mask:0xf bank_mask:0xf
	v_add_f32_dpp v246, v246, v246 row_mirror row_mask:0xf bank_mask:0xf
	v_add_f32_dpp v247, v247, v247 row_mirror row_mask:0xf bank_mask:0xf
	v_add_f32_dpp v248, v248, v248 row_mirror row_mask:0xf bank_mask:0xf
	v_add_f32_dpp v249, v249, v249 row_mirror row_mask:0xf bank_mask:0xf
	v_fmaak_f32 v246, v250, v246, 0x358637bd
	v_fmaak_f32 v247, v250, v247, 0x358637bd
	v_rsq_f32_e32 v246, v246
	v_rsq_f32_e32 v247, v247
	s_nop 0
	v_mul_f32_e32 v246, v130, v246
	v_mul_f32_e32 v247, v130, v247
	v_fmaak_f32 v248, v250, v248, 0x358637bd
	v_fmaak_f32 v249, v250, v249, 0x358637bd
	v_rsq_f32_e32 v248, v248
	v_rsq_f32_e32 v249, v249
	s_nop 0
	v_mul_f32_e32 v248, v130, v248
	v_mul_f32_e32 v249, v130, v249
	v_pk_mul_f32 v[112:113], v[112:113], v[246:247]
	v_pk_mul_f32 v[114:115], v[114:115], v[248:249]
	v_pk_mul_f32 v[112:113], v[112:113], v[132:133] op_sel_hi:[1,0]
	v_pk_mul_f32 v[114:115], v[114:115], v[132:133] op_sel_hi:[1,0]
	v_pk_mul_f32 v[116:117], v[116:117], v[246:247]
	v_pk_mul_f32 v[118:119], v[118:119], v[248:249]
	v_pk_mul_f32 v[116:117], v[116:117], v[134:135] op_sel_hi:[1,0]
	v_pk_mul_f32 v[118:119], v[118:119], v[134:135] op_sel_hi:[1,0]
	v_pk_mul_f32 v[120:121], v[120:121], v[246:247]
	v_pk_mul_f32 v[122:123], v[122:123], v[248:249]
	v_pk_mul_f32 v[120:121], v[120:121], v[136:137] op_sel_hi:[1,0]
	v_pk_mul_f32 v[122:123], v[122:123], v[136:137] op_sel_hi:[1,0]
	v_pk_mul_f32 v[124:125], v[124:125], v[246:247]
	v_pk_mul_f32 v[126:127], v[126:127], v[248:249]
	v_pk_mul_f32 v[124:125], v[124:125], v[138:139] op_sel_hi:[1,0]
	v_pk_mul_f32 v[126:127], v[126:127], v[138:139] op_sel_hi:[1,0]
; DI float shx(float v, int mask, int lane) { return __int_as_float(__builtin_amdgcn_ds_bpermute((lane ^ mask) << 2, __float_as_int(v))); }
; DI void epi_slab(const GemmCfg c, const f32x16 (&acc)[4], float* sW, const float* rss, const size_t row0, const int g, const int lane,
;                  float* const g_h, u16* const g_hb, float* const g_out, const int final_out) {
;     ...
;   } else {
;     const int c4 = l31 * 4;
;     const int col = g * 128 + c4;
; #pragma unroll 2
;     for (int it = 0; it < 16; ++it) {
;       const int r = hh + 2 * it;
;       const size_t row = row0 + r;
;       f32x4 v = *(const f32x4*)(sW + r * 132 + c4);
;       const float rs = c.use_rs ? rsqrtf(rss[r] * invK + 1e-6f) : 1.f;
;       if (c.epi == EPI_QKV) {
;         f32x4 x = v * rs;
;         float s = x[0] * x[0] + x[1] * x[1] + x[2] * x[2] + x[3] * x[3];
;         s += shx(s, 1, ln_); s += shx(s, 2, ln_); s += shx(s, 4, ln_); s += shx(s, 8, ln_);
;         if (g < c.nk_end) {
;           const float r2 = rsqrtf(s * (1.f / 64.f) + 1e-6f) * (g < 8 ? 0.125f * LOG2E : 1.f);
;           f32x4 gn = *(const f32x4*)(c.gain + (g < 8 ? 0 : 64) + (c4 & 63));
;           x = x * gn * r2;
;         }
;         *(u32x2*)(c.o16 + row * c.ldo + col) = MK2(pack2(x[0], x[1]), pack2(x[2], x[3]));
.Lqkv2_plain1:
	ds_write2_b32 v200, v96, v97 offset0:0 offset1:132
	ds_write2_b32 v201, v98, v99 offset0:0 offset1:132
	ds_write2_b32 v200, v100, v101 offset0:16 offset1:148
	ds_write2_b32 v201, v102, v103 offset0:16 offset1:148
	ds_write2_b32 v200, v104, v105 offset0:32 offset1:164
	ds_write2_b32 v201, v106, v107 offset0:32 offset1:164
	ds_write2_b32 v200, v108, v109 offset0:48 offset1:180
	ds_write2_b32 v201, v110, v111 offset0:48 offset1:180
	ds_write2_b32 v200, v112, v113 offset0:64 offset1:196
	ds_write2_b32 v201, v114, v115 offset0:64 offset1:196
	ds_write2_b32 v200, v116, v117 offset0:80 offset1:212
	ds_write2_b32 v201, v118, v119 offset0:80 offset1:212
	ds_write2_b32 v200, v120, v121 offset0:96 offset1:228
	ds_write2_b32 v201, v122, v123 offset0:96 offset1:228
	ds_write2_b32 v200, v124, v125 offset0:112 offset1:244
	ds_write2_b32 v201, v126, v127 offset0:112 offset1:244
	s_waitcnt lgkmcnt(0)
	ds_read_b128 v[64:67], v202
	ds_read_b128 v[68:71], v202 offset:1056
	ds_read_b128 v[72:75], v202 offset:2112
	ds_read_b128 v[76:79], v202 offset:3168
	ds_read_b128 v[80:83], v202 offset:4224
	ds_read_b128 v[84:87], v202 offset:5280
	ds_read_b128 v[88:91], v202 offset:6336
	ds_read_b128 v[92:95], v202 offset:7392
	ds_read_b128 v[96:99], v202 offset:8448
	s_waitcnt lgkmcnt(8)
	v_lshl_add_u64 v[206:207], v[204:205], 0, s[8:9]
	v_cvt_pk_bf16_f32 v64, v64, v65
	v_cvt_pk_bf16_f32 v65, v66, v67
	s_add_u32 s8, s8, s4
	s_addc_u32 s9, s9, 0
	global_store_dwordx2 v[206:207], v[64:65], off
	ds_read_b128 v[100:103], v202 offset:9504
	s_waitcnt lgkmcnt(8)
	v_lshl_add_u64 v[206:207], v[204:205], 0, s[8:9]
	v_cvt_pk_bf16_f32 v68, v68, v69
	v_cvt_pk_bf16_f32 v69, v70, v71
	s_add_u32 s8, s8, s4
	s_addc_u32 s9, s9, 0
	global_store_dwordx2 v[206:207], v[68:69], off
	ds_read_b128 v[104:107], v202 offset:10560
	s_waitcnt lgkmcnt(8)
	v_lshl_add_u64 v[206:207], v[204:205], 0, s[8:9]
	v_cvt_pk_bf16_f32 v72, v72, v73
	v_cvt_pk_bf16_f32 v73, v74, v75
	s_add_u32 s8, s8, s4
	s_addc_u32 s9, s9, 0
	global_store_dwordx2 v[206:207], v[72:73], off
	ds_read_b128 v[108:111], v202 offset:11616
	s_waitcnt lgkmcnt(8)
	v_lshl_add_u64 v[206:207], v[204:205], 0, s[8:9]
	v_cvt_pk_bf16_f32 v76, v76, v77
	v_cvt_pk_bf16_f32 v77, v78, v79
	s_add_u32 s8, s8, s4
	s_addc_u32 s9, s9, 0
	global_store_dwordx2 v[206:207], v[76:77], off
	ds_read_b128 v[112:115], v202 offset:12672
	s_waitcnt lgkmcnt(8)
	v_lshl_add_u64 v[206:207], v[204:205], 0, s[8:9]
	v_cvt_pk_bf16_f32 v80, v80, v81
	v_cvt_pk_bf16_f32 v81, v82, v83
	s_add_u32 s8, s8, s4
	s_addc_u32 s9, s9, 0
	global_store_dwordx2 v[206:207], v[80:81], off
	ds_read_b128 v[116:119], v202 offset:13728
	s_waitcnt lgkmcnt(8)
	v_lshl_add_u64 v[206:207], v[204:205], 0, s[8:9]
	v_cvt_pk_bf16_f32 v84, v84, v85
	v_cvt_pk_bf16_f32 v85, v86, v87
	s_add_u32 s8, s8, s4
	s_addc_u32 s9, s9, 0
	global_store_dwordx2 v[206:207], v[84:85], off
	ds_read_b128 v[120:123], v202 offset:14784
	s_waitcnt lgkmcnt(8)
	v_lshl_add_u64 v[206:207], v[204:205], 0, s[8:9]
	v_cvt_pk_bf16_f32 v88, v88, v89
	v_cvt_pk_bf16_f32 v89, v90, v91
	s_add_u32 s8, s8, s4
	s_addc_u32 s9, s9, 0
	global_store_dwordx2 v[206:207], v[88:89], off
	ds_read_b128 v[124:127], v202 offset:15840
	s_waitcnt lgkmcnt(8)
	v_lshl_add_u64 v[206:207], v[204:205], 0, s[8:9]
	v_cvt_pk_bf16_f32 v92, v92, v93
	v_cvt_pk_bf16_f32 v93, v94, v95
	s_add_u32 s8, s8, s4
	s_addc_u32 s9, s9, 0
	global_store_dwordx2 v[206:207], v[92:93], off
	s_waitcnt lgkmcnt(7)
	v_lshl_add_u64 v[206:207], v[204:205], 0, s[8:9]
	v_cvt_pk_bf16_f32 v96, v96, v97
	v_cvt_pk_bf16_f32 v97, v98, v99
	s_add_u32 s8, s8, s4
	s_addc_u32 s9, s9, 0
	global_store_dwordx2 v[206:207], v[96:97], off
	s_waitcnt lgkmcnt(6)
	v_lshl_add_u64 v[206:207], v[204:205], 0, s[8:9]
	v_cvt_pk_bf16_f32 v100, v100, v101
	v_cvt_pk_bf16_f32 v101, v102, v103
	s_add_u32 s8, s8, s4
	s_addc_u32 s9, s9, 0
	global_store_dwordx2 v[206:207], v[100:101], off
	s_waitcnt lgkmcnt(5)
	v_lshl_add_u64 v[206:207], v[204:205], 0, s[8:9]
	v_cvt_pk_bf16_f32 v104, v104, v105
	v_cvt_pk_bf16_f32 v105, v106, v107
	s_add_u32 s8, s8, s4
	s_addc_u32 s9, s9, 0
	global_store_dwordx2 v[206:207], v[104:105], off
	s_waitcnt lgkmcnt(4)
	v_lshl_add_u64 v[206:207], v[204:205], 0, s[8:9]
	v_cvt_pk_bf16_f32 v108, v108, v109
	v_cvt_pk_bf16_f32 v109, v110, v111
	s_add_u32 s8, s8, s4
	s_addc_u32 s9, s9, 0
	global_store_dwordx2 v[206:207], v[108:109], off
	s_waitcnt lgkmcnt(3)
	v_lshl_add_u64 v[206:207], v[204:205], 0, s[8:9]
	v_cvt_pk_bf16_f32 v112, v112, v113
	v_cvt_pk_bf16_f32 v113, v114, v115
	s_add_u32 s8, s8, s4
	s_addc_u32 s9, s9, 0
	global_store_dwordx2 v[206:207], v[112:113], off
	s_waitcnt lgkmcnt(2)
	v_lshl_add_u64 v[206:207], v[204:205], 0, s[8:9]
	v_cvt_pk_bf16_f32 v116, v116, v117
	v_cvt_pk_bf16_f32 v117, v118, v119
	s_add_u32 s8, s8, s4
	s_addc_u32 s9, s9, 0
	global_store_dwordx2 v[206:207], v[116:117], off
	s_waitcnt lgkmcnt(1)
	v_lshl_add_u64 v[206:207], v[204:205], 0, s[8:9]
	v_cvt_pk_bf16_f32 v120, v120, v121
	v_cvt_pk_bf16_f32 v121, v122, v123
	s_add_u32 s8, s8, s4
	s_addc_u32 s9, s9, 0
	global_store_dwordx2 v[206:207], v[120:121], off
	s_waitcnt lgkmcnt(0)
	v_lshl_add_u64 v[206:207], v[204:205], 0, s[8:9]
	v_cvt_pk_bf16_f32 v124, v124, v125
	v_cvt_pk_bf16_f32 v125, v126, v127
	s_add_u32 s8, s8, s4
	s_addc_u32 s9, s9, 0
	global_store_dwordx2 v[206:207], v[124:125], off
	v_pk_mul_f32 v[0:1], v[0:1], v[234:235]
	v_pk_mul_f32 v[2:3], v[2:3], v[236:237]
	v_pk_mul_f32 v[4:5], v[4:5], v[234:235]
	v_pk_mul_f32 v[6:7], v[6:7], v[236:237]
	v_pk_mul_f32 v[8:9], v[8:9], v[234:235]
	v_pk_mul_f32 v[10:11], v[10:11], v[236:237]
	v_pk_mul_f32 v[12:13], v[12:13], v[234:235]
	v_pk_mul_f32 v[14:15], v[14:15], v[236:237]
	v_pk_mul_f32 v[16:17], v[16:17], v[234:235]
	v_pk_mul_f32 v[18:19], v[18:19], v[236:237]
	v_pk_mul_f32 v[20:21], v[20:21], v[234:235]
	v_pk_mul_f32 v[22:23], v[22:23], v[236:237]
	v_pk_mul_f32 v[24:25], v[24:25], v[234:235]
	v_pk_mul_f32 v[26:27], v[26:27], v[236:237]
	v_pk_mul_f32 v[28:29], v[28:29], v[234:235]
	v_pk_mul_f32 v[30:31], v[30:31], v[236:237]
	s_and_b64 vcc, exec, s[72:73]
	s_cbranch_vccz .Lqkv2_plain2
; DI float shx(float v, int mask, int lane) { return __int_as_float(__builtin_amdgcn_ds_bpermute((lane ^ mask) << 2, __float_as_int(v))); }
; DI void epi_slab(const GemmCfg c, const f32x16 (&acc)[4], float* sW, const float* rss, const size_t row0, const int g, const int lane,
;                  float* const g_h, u16* const g_hb, float* const g_out, const int final_out) {
;     ...
;   } else {
;     const int c4 = l31 * 4;
;     const int col = g * 128 + c4;
; #pragma unroll 2
;     for (int it = 0; it < 16; ++it) {
;       const int r = hh + 2 * it;
;       const size_t row = row0 + r;
;       f32x4 v = *(const f32x4*)(sW + r * 132 + c4);
;       const float rs = c.use_rs ? rsqrtf(rss[r] * invK + 1e-6f) : 1.f;
;       if (c.epi == EPI_QKV) {
;         f32x4 x = v * rs;
;         float s = x[0] * x[0] + x[1] * x[1] + x[2] * x[2] + x[3] * x[3];
;         s += shx(s, 1, ln_); s += shx(s, 2, ln_); s += shx(s, 4, ln_); s += shx(s, 8, ln_);
;         if (g < c.nk_end) {
;           const float r2 = rsqrtf(s * (1.f / 64.f) + 1e-6f) * (g < 8 ? 0.125f * LOG2E : 1.f);
;           f32x4 gn = *(const f32x4*)(c.gain + (g < 8 ? 0 : 64) + (c4 & 63));
;           x = x * gn * r2;
;         }
;         *(u32x2*)(c.o16 + row * c.ldo + col) = MK2(pack2(x[0], x[1]), pack2(x[2], x[3]));
	v_mul_f32_e32 v246, v0, v0
	v_mul_f32_e32 v247, v1, v1
	v_mul_f32_e32 v248, v2, v2
	v_mul_f32_e32 v249, v3, v3
	v_fmac_f32_e32 v246, v4, v4
	v_fmac_f32_e32 v247, v5, v5
	v_fmac_f32_e32 v248, v6, v6
	v_fmac_f32_e32 v249, v7, v7
	v_fmac_f32_e32 v246, v8, v8
	v_fmac_f32_e32 v247, v9, v9
	v_fmac_f32_e32 v248, v10, v10
	v_fmac_f32_e32 v249, v11, v11
	v_fmac_f32_e32 v246, v12, v12
	v_fmac_f32_e32 v247, v13, v13
	v_fmac_f32_e32 v248, v14, v14
	v_fmac_f32_e32 v249, v15, v15
	v_add_f32_dpp v246, v246, v246 quad_perm:[1,0,3,2] row_mask:0xf bank_mask:0xf
	v_add_f32_dpp v247, v247, v247 quad_perm:[1,0,3,2] row_mask:0xf bank_mask:0xf
	v_add_f32_dpp v248, v248, v248 quad_perm:[1,0,3,2] row_mask:0xf bank_mask:0xf
	v_add_f32_dpp v249, v249, v249 quad_perm:[1,0,3,2] row_mask:0xf bank_mask:0xf
	v_add_f32_dpp v246, v246, v246 quad_perm:[2,3,0,1] row_mask:0xf bank_mask:0xf
	v_add_f32_dpp v247, v247, v247 quad_perm:[2,3,0,1] row_mask:0xf bank_mask:0xf
	v_add_f32_dpp v248, v248, v248 quad_perm:[2,3,0,1] row_mask:0xf bank_mask:0xf
	v_add_f32_dpp v249, v249, v249 quad_perm:[2,3,0,1] row_mask:0xf bank_mask:0xf
	v_add_f32_dpp v246, v246, v246 row_half_mirror row_mask:0xf bank_mask:0xf
	v_add_f32_dpp v247, v247, v247 row_half_mirror row_mask:0xf bank_mask:0xf
	v_add_f32_dpp v248, v248, v248 row_half_mirror row_mask:0xf bank_mask:0xf
	v_add_f32_dpp v249, v249, v249 row_half_mirror row_mask:0xf bank_mask:0xf
	v_add_f32_dpp v246, v246, v246 row_mirror row_mask:0xf bank_mask:0xf
	v_add_f32_dpp v247, v247, v247 row_mirror row_mask:0xf bank_mask:0xf
	v_add_f32_dpp v248, v248, v248 row_mirror row_mask:0xf bank_mask:0xf
	v_add_f32_dpp v249, v249, v249 row_mirror row_mask:0xf bank_mask:0xf
	v_fmaak_f32 v246, v250, v246, 0x358637bd
	v_fmaak_f32 v247, v250, v247, 0x358637bd
	v_rsq_f32_e32 v246, v246
	v_rsq_f32_e32 v247, v247
	s_nop 0
	v_mul_f32_e32 v246, v130, v246
	v_mul_f32_e32 v247, v130, v247
	v_fmaak_f32 v248, v250, v248, 0x358637bd
	v_fmaak_f32 v249, v250, v249, 0x358637bd
	v_rsq_f32_e32 v248, v248
	v_rsq_f32_e32 v249, v249
	s_nop 0
	v_mul_f32_e32 v248, v130, v248
	v_mul_f32_e32 v249, v130, v249
	v_pk_mul_f32 v[0:1], v[0:1], v[246:247]
	v_pk_mul_f32 v[2:3], v[2:3], v[248:249]
	v_pk_mul_f32 v[0:1], v[0:1], v[132:133] op_sel_hi:[1,0]
	v_pk_mul_f32 v[2:3], v[2:3], v[132:133] op_sel_hi:[1,0]
	v_pk_mul_f32 v[4:5], v[4:5], v[246:247]
	v_pk_mul_f32 v[6:7], v[6:7], v[248:249]
	v_pk_mul_f32 v[4:5], v[4:5], v[134:135] op_sel_hi:[1,0]
	v_pk_mul_f32 v[6:7], v[6:7], v[134:135] op_sel_hi:[1,0]
	v_pk_mul_f32 v[8:9], v[8:9], v[246:247]
	v_pk_mul_f32 v[10:11], v[10:11], v[248:249]
	v_pk_mul_f32 v[8:9], v[8:9], v[136:137] op_sel_hi:[1,0]
	v_pk_mul_f32 v[10:11], v[10:11], v[136:137] op_sel_hi:[1,0]
	v_pk_mul_f32 v[12:13], v[12:13], v[246:247]
	v_pk_mul_f32 v[14:15], v[14:15], v[248:249]
	v_pk_mul_f32 v[12:13], v[12:13], v[138:139] op_sel_hi:[1,0]
	v_pk_mul_f32 v[14:15], v[14:15], v[138:139] op_sel_hi:[1,0]
	v_mul_f32_e32 v246, v16, v16
	v_mul_f32_e32 v247, v17, v17
	v_mul_f32_e32 v248, v18, v18
	v_mul_f32_e32 v249, v19, v19
	v_fmac_f32_e32 v246, v20, v20
	v_fmac_f32_e32 v247, v21, v21
	v_fmac_f32_e32 v248, v22, v22
	v_fmac_f32_e32 v249, v23, v23
	v_fmac_f32_e32 v246, v24, v24
	v_fmac_f32_e32 v247, v25, v25
	v_fmac_f32_e32 v248, v26, v26
	v_fmac_f32_e32 v249, v27, v27
	v_fmac_f32_e32 v246, v28, v28
	v_fmac_f32_e32 v247, v29, v29
	v_fmac_f32_e32 v248, v30, v30
	v_fmac_f32_e32 v249, v31, v31
	v_add_f32_dpp v246, v246, v246 quad_perm:[1,0,3,2] row_mask:0xf bank_mask:0xf
	v_add_f32_dpp v247, v247, v247 quad_perm:[1,0,3,2] row_mask:0xf bank_mask:0xf
	v_add_f32_dpp v248, v248, v248 quad_perm:[1,0,3,2] row_mask:0xf bank_mask:0xf
	v_add_f32_dpp v249, v249, v249 quad_perm:[1,0,3,2] row_mask:0xf bank_mask:0xf
	v_add_f32_dpp v246, v246, v246 quad_perm:[2,3,0,1] row_mask:0xf bank_mask:0xf
	v_add_f32_dpp v247, v247, v247 quad_perm:[2,3,0,1] row_mask:0xf bank_mask:0xf
	v_add_f32_dpp v248, v248, v248 quad_perm:[2,3,0,1] row_mask:0xf bank_mask:0xf
	v_add_f32_dpp v249, v249, v249 quad_perm:[2,3,0,1] row_mask:0xf bank_mask:0xf
	v_add_f32_dpp v246, v246, v246 row_half_mirror row_mask:0xf bank_mask:0xf
	v_add_f32_dpp v247, v247, v247 row_half_mirror row_mask:0xf bank_mask:0xf
	v_add_f32_dpp v248, v248, v248 row_half_mirror row_mask:0xf bank_mask:0xf
	v_add_f32_dpp v249, v249, v249 row_half_mirror row_mask:0xf bank_mask:0xf
	v_add_f32_dpp v246, v246, v246 row_mirror row_mask:0xf bank_mask:0xf
	v_add_f32_dpp v247, v247, v247 row_mirror row_mask:0xf bank_mask:0xf
	v_add_f32_dpp v248, v248, v248 row_mirror row_mask:0xf bank_mask:0xf
	v_add_f32_dpp v249, v249, v249 row_mirror row_mask:0xf bank_mask:0xf
	v_fmaak_f32 v246, v250, v246, 0x358637bd
	v_fmaak_f32 v247, v250, v247, 0x358637bd
	v_rsq_f32_e32 v246, v246
	v_rsq_f32_e32 v247, v247
	s_nop 0
	v_mul_f32_e32 v246, v130, v246
	v_mul_f32_e32 v247, v130, v247
	v_fmaak_f32 v248, v250, v248, 0x358637bd
	v_fmaak_f32 v249, v250, v249, 0x358637bd
	v_rsq_f32_e32 v248, v248
	v_rsq_f32_e32 v249, v249
	s_nop 0
	v_mul_f32_e32 v248, v130, v248
	v_mul_f32_e32 v249, v130, v249
	v_pk_mul_f32 v[16:17], v[16:17], v[246:247]
	v_pk_mul_f32 v[18:19], v[18:19], v[248:249]
	v_pk_mul_f32 v[16:17], v[16:17], v[132:133] op_sel_hi:[1,0]
	v_pk_mul_f32 v[18:19], v[18:19], v[132:133] op_sel_hi:[1,0]
	v_pk_mul_f32 v[20:21], v[20:21], v[246:247]
	v_pk_mul_f32 v[22:23], v[22:23], v[248:249]
	v_pk_mul_f32 v[20:21], v[20:21], v[134:135] op_sel_hi:[1,0]
	v_pk_mul_f32 v[22:23], v[22:23], v[134:135] op_sel_hi:[1,0]
	v_pk_mul_f32 v[24:25], v[24:25], v[246:247]
	v_pk_mul_f32 v[26:27], v[26:27], v[248:249]
	v_pk_mul_f32 v[24:25], v[24:25], v[136:137] op_sel_hi:[1,0]
	v_pk_mul_f32 v[26:27], v[26:27], v[136:137] op_sel_hi:[1,0]
	v_pk_mul_f32 v[28:29], v[28:29], v[246:247]
	v_pk_mul_f32 v[30:31], v[30:31], v[248:249]
	v_pk_mul_f32 v[28:29], v[28:29], v[138:139] op_sel_hi:[1,0]
	v_pk_mul_f32 v[30:31], v[30:31], v[138:139] op_sel_hi:[1,0]
; DI float shx(float v, int mask, int lane) { return __int_as_float(__builtin_amdgcn_ds_bpermute((lane ^ mask) << 2, __float_as_int(v))); }
; DI void epi_slab(const GemmCfg c, const f32x16 (&acc)[4], float* sW, const float* rss, const size_t row0, const int g, const int lane,
;                  float* const g_h, u16* const g_hb, float* const g_out, const int final_out) {
;     ...
;   } else {
;     const int c4 = l31 * 4;
;     const int col = g * 128 + c4;
; #pragma unroll 2
;     for (int it = 0; it < 16; ++it) {
;       const int r = hh + 2 * it;
;       const size_t row = row0 + r;
;       f32x4 v = *(const f32x4*)(sW + r * 132 + c4);
;       const float rs = c.use_rs ? rsqrtf(rss[r] * invK + 1e-6f) : 1.f;
;       if (c.epi == EPI_QKV) {
;         f32x4 x = v * rs;
;         float s = x[0] * x[0] + x[1] * x[1] + x[2] * x[2] + x[3] * x[3];
;         s += shx(s, 1, ln_); s += shx(s, 2, ln_); s += shx(s, 4, ln_); s += shx(s, 8, ln_);
;         if (g < c.nk_end) {
;           const float r2 = rsqrtf(s * (1.f / 64.f) + 1e-6f) * (g < 8 ? 0.125f * LOG2E : 1.f);
;           f32x4 gn = *(const f32x4*)(c.gain + (g < 8 ? 0 : 64) + (c4 & 63));
;           x = x * gn * r2;
;         }
;         *(u32x2*)(c.o16 + row * c.ldo + col) = MK2(pack2(x[0], x[1]), pack2(x[2], x[3]));
.Lqkv2_plain2:
	ds_write2_b32 v198, v0, v1 offset0:0 offset1:132
	ds_write2_b32 v199, v2, v3 offset0:0 offset1:132
	ds_write2_b32 v198, v4, v5 offset0:16 offset1:148
	ds_write2_b32 v199, v6, v7 offset0:16 offset1:148
	ds_write2_b32 v198, v8, v9 offset0:32 offset1:164
	ds_write2_b32 v199, v10, v11 offset0:32 offset1:164
	ds_write2_b32 v198, v12, v13 offset0:48 offset1:180
	ds_write2_b32 v199, v14, v15 offset0:48 offset1:180
	ds_write2_b32 v198, v16, v17 offset0:64 offset1:196
	ds_write2_b32 v199, v18, v19 offset0:64 offset1:196
	ds_write2_b32 v198, v20, v21 offset0:80 offset1:212
	ds_write2_b32 v199, v22, v23 offset0:80 offset1:212
	ds_write2_b32 v198, v24, v25 offset0:96 offset1:228
	ds_write2_b32 v199, v26, v27 offset0:96 offset1:228
	ds_write2_b32 v198, v28, v29 offset0:112 offset1:244
	ds_write2_b32 v199, v30, v31 offset0:112 offset1:244
	v_pk_mul_f32 v[32:33], v[32:33], v[238:239]
	v_pk_mul_f32 v[34:35], v[34:35], v[240:241]
	v_pk_mul_f32 v[36:37], v[36:37], v[238:239]
	v_pk_mul_f32 v[38:39], v[38:39], v[240:241]
	v_pk_mul_f32 v[40:41], v[40:41], v[238:239]
	v_pk_mul_f32 v[42:43], v[42:43], v[240:241]
	v_pk_mul_f32 v[44:45], v[44:45], v[238:239]
	v_pk_mul_f32 v[46:47], v[46:47], v[240:241]
	v_pk_mul_f32 v[48:49], v[48:49], v[238:239]
	v_pk_mul_f32 v[50:51], v[50:51], v[240:241]
	v_pk_mul_f32 v[52:53], v[52:53], v[238:239]
	v_pk_mul_f32 v[54:55], v[54:55], v[240:241]
	v_pk_mul_f32 v[56:57], v[56:57], v[238:239]
	v_pk_mul_f32 v[58:59], v[58:59], v[240:241]
	v_pk_mul_f32 v[60:61], v[60:61], v[238:239]
	v_pk_mul_f32 v[62:63], v[62:63], v[240:241]
	s_and_b64 vcc, exec, s[72:73]
	s_cbranch_vccz .Lqkv2_plain3
; DI float shx(float v, int mask, int lane) { return __int_as_float(__builtin_amdgcn_ds_bpermute((lane ^ mask) << 2, __float_as_int(v))); }
; DI void epi_slab(const GemmCfg c, const f32x16 (&acc)[4], float* sW, const float* rss, const size_t row0, const int g, const int lane,
;                  float* const g_h, u16* const g_hb, float* const g_out, const int final_out) {
;     ...
;   } else {
;     const int c4 = l31 * 4;
;     const int col = g * 128 + c4;
; #pragma unroll 2
;     for (int it = 0; it < 16; ++it) {
;       const int r = hh + 2 * it;
;       const size_t row = row0 + r;
;       f32x4 v = *(const f32x4*)(sW + r * 132 + c4);
;       const float rs = c.use_rs ? rsqrtf(rss[r] * invK + 1e-6f) : 1.f;
;       if (c.epi == EPI_QKV) {
;         f32x4 x = v * rs;
;         float s = x[0] * x[0] + x[1] * x[1] + x[2] * x[2] + x[3] * x[3];
;         s += shx(s, 1, ln_); s += shx(s, 2, ln_); s += shx(s, 4, ln_); s += shx(s, 8, ln_);
;         if (g < c.nk_end) {
;           const float r2 = rsqrtf(s * (1.f / 64.f) + 1e-6f) * (g < 8 ? 0.125f * LOG2E : 1.f);
;           f32x4 gn = *(const f32x4*)(c.gain + (g < 8 ? 0 : 64) + (c4 & 63));
;           x = x * gn * r2;
;         }
;         *(u32x2*)(c.o16 + row * c.ldo + col) = MK2(pack2(x[0], x[1]), pack2(x[2], x[3]));
	v_mul_f32_e32 v246, v32, v32
	v_mul_f32_e32 v247, v33, v33
	v_mul_f32_e32 v248, v34, v34
	v_mul_f32_e32 v249, v35, v35
	v_fmac_f32_e32 v246, v36, v36
	v_fmac_f32_e32 v247, v37, v37
	v_fmac_f32_e32 v248, v38, v38
	v_fmac_f32_e32 v249, v39, v39
	v_fmac_f32_e32 v246, v40, v40
	v_fmac_f32_e32 v247, v41, v41
	v_fmac_f32_e32 v248, v42, v42
	v_fmac_f32_e32 v249, v43, v43
	v_fmac_f32_e32 v246, v44, v44
	v_fmac_f32_e32 v247, v45, v45
	v_fmac_f32_e32 v248, v46, v46
	v_fmac_f32_e32 v249, v47, v47
	v_add_f32_dpp v246, v246, v246 quad_perm:[1,0,3,2] row_mask:0xf bank_mask:0xf
	v_add_f32_dpp v247, v247, v247 quad_perm:[1,0,3,2] row_mask:0xf bank_mask:0xf
	v_add_f32_dpp v248, v248, v248 quad_perm:[1,0,3,2] row_mask:0xf bank_mask:0xf
	v_add_f32_dpp v249, v249, v249 quad_perm:[1,0,3,2] row_mask:0xf bank_mask:0xf
	v_add_f32_dpp v246, v246, v246 quad_perm:[2,3,0,1] row_mask:0xf bank_mask:0xf
	v_add_f32_dpp v247, v247, v247 quad_perm:[2,3,0,1] row_mask:0xf bank_mask:0xf
	v_add_f32_dpp v248, v248, v248 quad_perm:[2,3,0,1] row_mask:0xf bank_mask:0xf
	v_add_f32_dpp v249, v249, v249 quad_perm:[2,3,0,1] row_mask:0xf bank_mask:0xf
	v_add_f32_dpp v246, v246, v246 row_half_mirror row_mask:0xf bank_mask:0xf
	v_add_f32_dpp v247, v247, v247 row_half_mirror row_mask:0xf bank_mask:0xf
	v_add_f32_dpp v248, v248, v248 row_half_mirror row_mask:0xf bank_mask:0xf
	v_add_f32_dpp v249, v249, v249 row_half_mirror row_mask:0xf bank_mask:0xf
	v_add_f32_dpp v246, v246, v246 row_mirror row_mask:0xf bank_mask:0xf
	v_add_f32_dpp v247, v247, v247 row_mirror row_mask:0xf bank_mask:0xf
	v_add_f32_dpp v248, v248, v248 row_mirror row_mask:0xf bank_mask:0xf
	v_add_f32_dpp v249, v249, v249 row_mirror row_mask:0xf bank_mask:0xf
	v_fmaak_f32 v246, v250, v246, 0x358637bd
	v_fmaak_f32 v247, v250, v247, 0x358637bd
	v_rsq_f32_e32 v246, v246
	v_rsq_f32_e32 v247, v247
	s_nop 0
	v_mul_f32_e32 v246, v130, v246
	v_mul_f32_e32 v247, v130, v247
	v_fmaak_f32 v248, v250, v248, 0x358637bd
	v_fmaak_f32 v249, v250, v249, 0x358637bd
	v_rsq_f32_e32 v248, v248
	v_rsq_f32_e32 v249, v249
	s_nop 0
	v_mul_f32_e32 v248, v130, v248
	v_mul_f32_e32 v249, v130, v249
	v_pk_mul_f32 v[32:33], v[32:33], v[246:247]
	v_pk_mul_f32 v[34:35], v[34:35], v[248:249]
	v_pk_mul_f32 v[32:33], v[32:33], v[132:133] op_sel_hi:[1,0]
	v_pk_mul_f32 v[34:35], v[34:35], v[132:133] op_sel_hi:[1,0]
	v_pk_mul_f32 v[36:37], v[36:37], v[246:247]
	v_pk_mul_f32 v[38:39], v[38:39], v[248:249]
	v_pk_mul_f32 v[36:37], v[36:37], v[134:135] op_sel_hi:[1,0]
	v_pk_mul_f32 v[38:39], v[38:39], v[134:135] op_sel_hi:[1,0]
	v_pk_mul_f32 v[40:41], v[40:41], v[246:247]
	v_pk_mul_f32 v[42:43], v[42:43], v[248:249]
	v_pk_mul_f32 v[40:41], v[40:41], v[136:137] op_sel_hi:[1,0]
	v_pk_mul_f32 v[42:43], v[42:43], v[136:137] op_sel_hi:[1,0]
	v_pk_mul_f32 v[44:45], v[44:45], v[246:247]
	v_pk_mul_f32 v[46:47], v[46:47], v[248:249]
	v_pk_mul_f32 v[44:45], v[44:45], v[138:139] op_sel_hi:[1,0]
	v_pk_mul_f32 v[46:47], v[46:47], v[138:139] op_sel_hi:[1,0]
	v_mul_f32_e32 v246, v48, v48
	v_mul_f32_e32 v247, v49, v49
	v_mul_f32_e32 v248, v50, v50
	v_mul_f32_e32 v249, v51, v51
	v_fmac_f32_e32 v246, v52, v52
	v_fmac_f32_e32 v247, v53, v53
	v_fmac_f32_e32 v248, v54, v54
	v_fmac_f32_e32 v249, v55, v55
	v_fmac_f32_e32 v246, v56, v56
	v_fmac_f32_e32 v247, v57, v57
	v_fmac_f32_e32 v248, v58, v58
	v_fmac_f32_e32 v249, v59, v59
	v_fmac_f32_e32 v246, v60, v60
	v_fmac_f32_e32 v247, v61, v61
	v_fmac_f32_e32 v248, v62, v62
	v_fmac_f32_e32 v249, v63, v63
	v_add_f32_dpp v246, v246, v246 quad_perm:[1,0,3,2] row_mask:0xf bank_mask:0xf
	v_add_f32_dpp v247, v247, v247 quad_perm:[1,0,3,2] row_mask:0xf bank_mask:0xf
	v_add_f32_dpp v248, v248, v248 quad_perm:[1,0,3,2] row_mask:0xf bank_mask:0xf
	v_add_f32_dpp v249, v249, v249 quad_perm:[1,0,3,2] row_mask:0xf bank_mask:0xf
	v_add_f32_dpp v246, v246, v246 quad_perm:[2,3,0,1] row_mask:0xf bank_mask:0xf
	v_add_f32_dpp v247, v247, v247 quad_perm:[2,3,0,1] row_mask:0xf bank_mask:0xf
	v_add_f32_dpp v248, v248, v248 quad_perm:[2,3,0,1] row_mask:0xf bank_mask:0xf
	v_add_f32_dpp v249, v249, v249 quad_perm:[2,3,0,1] row_mask:0xf bank_mask:0xf
	v_add_f32_dpp v246, v246, v246 row_half_mirror row_mask:0xf bank_mask:0xf
	v_add_f32_dpp v247, v247, v247 row_half_mirror row_mask:0xf bank_mask:0xf
	v_add_f32_dpp v248, v248, v248 row_half_mirror row_mask:0xf bank_mask:0xf
	v_add_f32_dpp v249, v249, v249 row_half_mirror row_mask:0xf bank_mask:0xf
	v_add_f32_dpp v246, v246, v246 row_mirror row_mask:0xf bank_mask:0xf
	v_add_f32_dpp v247, v247, v247 row_mirror row_mask:0xf bank_mask:0xf
	v_add_f32_dpp v248, v248, v248 row_mirror row_mask:0xf bank_mask:0xf
	v_add_f32_dpp v249, v249, v249 row_mirror row_mask:0xf bank_mask:0xf
	v_fmaak_f32 v246, v250, v246, 0x358637bd
	v_fmaak_f32 v247, v250, v247, 0x358637bd
	v_rsq_f32_e32 v246, v246
	v_rsq_f32_e32 v247, v247
	s_nop 0
	v_mul_f32_e32 v246, v130, v246
	v_mul_f32_e32 v247, v130, v247
	v_fmaak_f32 v248, v250, v248, 0x358637bd
	v_fmaak_f32 v249, v250, v249, 0x358637bd
	v_rsq_f32_e32 v248, v248
	v_rsq_f32_e32 v249, v249
	s_nop 0
	v_mul_f32_e32 v248, v130, v248
	v_mul_f32_e32 v249, v130, v249
	v_pk_mul_f32 v[48:49], v[48:49], v[246:247]
	v_pk_mul_f32 v[50:51], v[50:51], v[248:249]
	v_pk_mul_f32 v[48:49], v[48:49], v[132:133] op_sel_hi:[1,0]
	v_pk_mul_f32 v[50:51], v[50:51], v[132:133] op_sel_hi:[1,0]
	v_pk_mul_f32 v[52:53], v[52:53], v[246:247]
	v_pk_mul_f32 v[54:55], v[54:55], v[248:249]
	v_pk_mul_f32 v[52:53], v[52:53], v[134:135] op_sel_hi:[1,0]
	v_pk_mul_f32 v[54:55], v[54:55], v[134:135] op_sel_hi:[1,0]
	v_pk_mul_f32 v[56:57], v[56:57], v[246:247]
	v_pk_mul_f32 v[58:59], v[58:59], v[248:249]
	v_pk_mul_f32 v[56:57], v[56:57], v[136:137] op_sel_hi:[1,0]
	v_pk_mul_f32 v[58:59], v[58:59], v[136:137] op_sel_hi:[1,0]
	v_pk_mul_f32 v[60:61], v[60:61], v[246:247]
	v_pk_mul_f32 v[62:63], v[62:63], v[248:249]
	v_pk_mul_f32 v[60:61], v[60:61], v[138:139] op_sel_hi:[1,0]
	v_pk_mul_f32 v[62:63], v[62:63], v[138:139] op_sel_hi:[1,0]

; DI float shx(float v, int mask, int lane) { return __int_as_float(__builtin_amdgcn_ds_bpermute((lane ^ mask) << 2, __float_as_int(v))); }
; DI void epi_slab(const GemmCfg c, const f32x16 (&acc)[4], float* sW, const float* rss, const size_t row0, const int g, const int lane,
;                  float* const g_h, u16* const g_hb, float* const g_out, const int final_out) {
;     ...
;     for (int it = 0; it < 16; ++it) {
;       const int r = hh + 2 * it;
;       const size_t row = row0 + r;
;       f32x4 v = *(const f32x4*)(sW + r * 132 + c4);
;       const float rs = c.use_rs ? rsqrtf(rss[r] * invK + 1e-6f) : 1.f;
;     ...
;       } else if (c.epi == EPI_QABS) {
;         f32x4 x = v * rs;
;         float s = x[0] * x[0] + x[1] * x[1] + x[2] * x[2] + x[3] * x[3];
;         s += shx(s, 1, ln_); s += shx(s, 2, ln_); s += shx(s, 4, ln_); s += shx(s, 8, ln_); s += shx(s, 16, ln_);
;         if (l31 == 0) c.f0[row * 32 + g] = s;
;         *(u32x2*)(c.o16 + row * 4096 + col) = MK2(pack2(x[0], x[1]), pack2(x[2], x[3]));
.Lqabs2:
	v_and_b32_e32 v222, 15, v185
	v_lshrrev_b32_e32 v223, 4, v185
	s_lshl_b32 s4, s86, 2
	s_add_i32 s4, s4, 0x24000
	v_lshl_add_u32 v224, v223, 4, s4
	ds_read_b128 v[226:229], v224
	ds_read_b128 v[230:233], v224 offset:64
	ds_read_b128 v[234:237], v224 offset:128
	ds_read_b128 v[238:241], v224 offset:192
	v_mul_u32_u24_e32 v198, 0x840, v223
	v_lshl_add_u32 v198, v222, 2, v198
	v_add_u32_e32 v198, s53, v198
	v_add_u32_e32 v199, 0x420, v198
	v_add_u32_e32 v200, 0x2100, v198
	v_add_u32_e32 v201, 0x2520, v198
	v_lshrrev_b32_e32 v202, 5, v185
	v_and_b32_e32 v206, 31, v185
	v_mul_u32_u24_e32 v204, 0x210, v202
	v_lshl_add_u32 v204, v206, 4, v204
	v_add_u32_e32 v250, s53, v204
	v_add_u32_e32 v204, s6, v202
	v_lshlrev_b32_e32 v204, 13, v204
	v_lshl_add_u32 v206, v206, 2, s64
	v_lshl_add_u32 v204, v206, 1, v204
	v_mov_b32_e32 v205, 0
	v_lshl_add_u64 v[204:205], v[204:205], 0, s[56:57]
	v_mov_b32_e32 v202, v250
	v_mov_b32_e32 v250, 0x3c800000
	v_lshl_add_u32 v242, v223, 2, s6
	v_lshlrev_b32_e32 v242, 7, v242
	s_lshr_b32 s5, s64, 5
	v_add_u32_e32 v242, s5, v242
	v_mov_b32_e32 v243, 0
	v_lshl_add_u64 v[242:243], v[242:243], 0, s[76:77]
	v_mov_b32_e32 v244, 0x1000
	v_mov_b32_e32 v245, 0
	s_movk_i32 s4, 0x4000
	s_mov_b64 s[8:9], 0
	s_waitcnt lgkmcnt(0)
	v_fmaak_f32 v226, v191, v226, 0x358637bd
	v_fmaak_f32 v227, v191, v227, 0x358637bd
	v_rsq_f32_e32 v226, v226
	v_rsq_f32_e32 v227, v227
	s_nop 0
	v_fmaak_f32 v228, v191, v228, 0x358637bd
	v_fmaak_f32 v229, v191, v229, 0x358637bd
	v_rsq_f32_e32 v228, v228
	v_rsq_f32_e32 v229, v229
	s_nop 0
	v_fmaak_f32 v230, v191, v230, 0x358637bd
	v_fmaak_f32 v231, v191, v231, 0x358637bd
	v_rsq_f32_e32 v230, v230
	v_rsq_f32_e32 v231, v231
	s_nop 0
	v_fmaak_f32 v232, v191, v232, 0x358637bd
	v_fmaak_f32 v233, v191, v233, 0x358637bd
	v_rsq_f32_e32 v232, v232
	v_rsq_f32_e32 v233, v233
	s_nop 0
	v_fmaak_f32 v234, v191, v234, 0x358637bd
	v_fmaak_f32 v235, v191, v235, 0x358637bd
	v_rsq_f32_e32 v234, v234
	v_rsq_f32_e32 v235, v235
	s_nop 0
	v_fmaak_f32 v236, v191, v236, 0x358637bd
	v_fmaak_f32 v237, v191, v237, 0x358637bd
	v_rsq_f32_e32 v236, v236
	v_rsq_f32_e32 v237, v237
	s_nop 0
	v_fmaak_f32 v238, v191, v238, 0x358637bd
	v_fmaak_f32 v239, v191, v239, 0x358637bd
	v_rsq_f32_e32 v238, v238
	v_rsq_f32_e32 v239, v239
	s_nop 0
	v_fmaak_f32 v240, v191, v240, 0x358637bd
	v_fmaak_f32 v241, v191, v241, 0x358637bd
	v_rsq_f32_e32 v240, v240
	v_rsq_f32_e32 v241, v241
	s_nop 0
	v_pk_mul_f32 v[64:65], v[64:65], v[226:227]
	v_pk_mul_f32 v[66:67], v[66:67], v[228:229]
	v_pk_mul_f32 v[68:69], v[68:69], v[226:227]
	v_pk_mul_f32 v[70:71], v[70:71], v[228:229]
	v_pk_mul_f32 v[72:73], v[72:73], v[226:227]
	v_pk_mul_f32 v[74:75], v[74:75], v[228:229]
	v_pk_mul_f32 v[76:77], v[76:77], v[226:227]
	v_pk_mul_f32 v[78:79], v[78:79], v[228:229]
	v_pk_mul_f32 v[80:81], v[80:81], v[226:227]
	v_pk_mul_f32 v[82:83], v[82:83], v[228:229]
	v_pk_mul_f32 v[84:85], v[84:85], v[226:227]
	v_pk_mul_f32 v[86:87], v[86:87], v[228:229]
	v_pk_mul_f32 v[88:89], v[88:89], v[226:227]
	v_pk_mul_f32 v[90:91], v[90:91], v[228:229]
	v_pk_mul_f32 v[92:93], v[92:93], v[226:227]
	v_pk_mul_f32 v[94:95], v[94:95], v[228:229]
	v_mul_f32_e32 v246, v64, v64
	v_mul_f32_e32 v247, v65, v65
	v_mul_f32_e32 v248, v66, v66
	v_mul_f32_e32 v249, v67, v67
	v_fmac_f32_e32 v246, v68, v68
	v_fmac_f32_e32 v247, v69, v69
	v_fmac_f32_e32 v248, v70, v70
	v_fmac_f32_e32 v249, v71, v71
	v_fmac_f32_e32 v246, v72, v72
	v_fmac_f32_e32 v247, v73, v73
	v_fmac_f32_e32 v248, v74, v74
	v_fmac_f32_e32 v249, v75, v75
	v_fmac_f32_e32 v246, v76, v76
	v_fmac_f32_e32 v247, v77, v77
	v_fmac_f32_e32 v248, v78, v78
	v_fmac_f32_e32 v249, v79, v79
	v_fmac_f32_e32 v246, v80, v80
	v_fmac_f32_e32 v247, v81, v81
	v_fmac_f32_e32 v248, v82, v82
	v_fmac_f32_e32 v249, v83, v83
	v_fmac_f32_e32 v246, v84, v84
	v_fmac_f32_e32 v247, v85, v85
	v_fmac_f32_e32 v248, v86, v86
	v_fmac_f32_e32 v249, v87, v87
	v_fmac_f32_e32 v246, v88, v88
	v_fmac_f32_e32 v247, v89, v89
	v_fmac_f32_e32 v248, v90, v90
	v_fmac_f32_e32 v249, v91, v91
	v_fmac_f32_e32 v246, v92, v92
	v_fmac_f32_e32 v247, v93, v93
	v_fmac_f32_e32 v248, v94, v94
	v_fmac_f32_e32 v249, v95, v95
	v_add_f32_dpp v246, v246, v246 quad_perm:[1,0,3,2] row_mask:0xf bank_mask:0xf
	v_add_f32_dpp v247, v247, v247 quad_perm:[1,0,3,2] row_mask:0xf bank_mask:0xf
	v_add_f32_dpp v248, v248, v248 quad_perm:[1,0,3,2] row_mask:0xf bank_mask:0xf
	v_add_f32_dpp v249, v249, v249 quad_perm:[1,0,3,2] row_mask:0xf bank_mask:0xf
	v_add_f32_dpp v246, v246, v246 quad_perm:[2,3,0,1] row_mask:0xf bank_mask:0xf
	v_add_f32_dpp v247, v247, v247 quad_perm:[2,3,0,1] row_mask:0xf bank_mask:0xf
	v_add_f32_dpp v248, v248, v248 quad_perm:[2,3,0,1] row_mask:0xf bank_mask:0xf
	v_add_f32_dpp v249, v249, v249 quad_perm:[2,3,0,1] row_mask:0xf bank_mask:0xf
	v_add_f32_dpp v246, v246, v246 row_half_mirror row_mask:0xf bank_mask:0xf
	v_add_f32_dpp v247, v247, v247 row_half_mirror row_mask:0xf bank_mask:0xf
	v_add_f32_dpp v248, v248, v248 row_half_mirror row_mask:0xf bank_mask:0xf
	v_add_f32_dpp v249, v249, v249 row_half_mirror row_mask:0xf bank_mask:0xf
	v_add_f32_dpp v246, v246, v246 row_mirror row_mask:0xf bank_mask:0xf
	v_add_f32_dpp v247, v247, v247 row_mirror row_mask:0xf bank_mask:0xf
	v_add_f32_dpp v248, v248, v248 row_mirror row_mask:0xf bank_mask:0xf
	v_add_f32_dpp v249, v249, v249 row_mirror row_mask:0xf bank_mask:0xf
	global_store_dword v[242:243], v246, off offset:0
	global_store_dword v[242:243], v247, off offset:128
	global_store_dword v[242:243], v248, off offset:256
	global_store_dword v[242:243], v249, off offset:384
	ds_write2_b32 v198, v64, v65 offset0:0 offset1:132
	ds_write2_b32 v199, v66, v67 offset0:0 offset1:132
; DI float shx(float v, int mask, int lane) { return __int_as_float(__builtin_amdgcn_ds_bpermute((lane ^ mask) << 2, __float_as_int(v))); }
; DI void epi_slab(const GemmCfg c, const f32x16 (&acc)[4], float* sW, const float* rss, const size_t row0, const int g, const int lane,
;                  float* const g_h, u16* const g_hb, float* const g_out, const int final_out) {
;     ...
;       } else if (c.epi == EPI_QABS) {
;         f32x4 x = v * rs;
;         float s = x[0] * x[0] + x[1] * x[1] + x[2] * x[2] + x[3] * x[3];
;         s += shx(s, 1, ln_); s += shx(s, 2, ln_); s += shx(s, 4, ln_); s += shx(s, 8, ln_); s += shx(s, 16, ln_);
;         if (l31 == 0) c.f0[row * 32 + g] = s;
;         *(u32x2*)(c.o16 + row * 4096 + col) = MK2(pack2(x[0], x[1]), pack2(x[2], x[3]));
	ds_write2_b32 v198, v68, v69 offset0:16 offset1:148
	ds_write2_b32 v199, v70, v71 offset0:16 offset1:148
	ds_write2_b32 v198, v72, v73 offset0:32 offset1:164
	ds_write2_b32 v199, v74, v75 offset0:32 offset1:164
	ds_write2_b32 v198, v76, v77 offset0:48 offset1:180
	ds_write2_b32 v199, v78, v79 offset0:48 offset1:180
	ds_write2_b32 v198, v80, v81 offset0:64 offset1:196
	ds_write2_b32 v199, v82, v83 offset0:64 offset1:196
	ds_write2_b32 v198, v84, v85 offset0:80 offset1:212
	ds_write2_b32 v199, v86, v87 offset0:80 offset1:212
	ds_write2_b32 v198, v88, v89 offset0:96 offset1:228
	ds_write2_b32 v199, v90, v91 offset0:96 offset1:228
	ds_write2_b32 v198, v92, v93 offset0:112 offset1:244
	ds_write2_b32 v199, v94, v95 offset0:112 offset1:244
	v_pk_mul_f32 v[96:97], v[96:97], v[230:231]
	v_pk_mul_f32 v[98:99], v[98:99], v[232:233]
	v_pk_mul_f32 v[100:101], v[100:101], v[230:231]
	v_pk_mul_f32 v[102:103], v[102:103], v[232:233]
	v_pk_mul_f32 v[104:105], v[104:105], v[230:231]
	v_pk_mul_f32 v[106:107], v[106:107], v[232:233]
	v_pk_mul_f32 v[108:109], v[108:109], v[230:231]
	v_pk_mul_f32 v[110:111], v[110:111], v[232:233]
	v_pk_mul_f32 v[112:113], v[112:113], v[230:231]
	v_pk_mul_f32 v[114:115], v[114:115], v[232:233]
	v_pk_mul_f32 v[116:117], v[116:117], v[230:231]
	v_pk_mul_f32 v[118:119], v[118:119], v[232:233]
	v_pk_mul_f32 v[120:121], v[120:121], v[230:231]
	v_pk_mul_f32 v[122:123], v[122:123], v[232:233]
	v_pk_mul_f32 v[124:125], v[124:125], v[230:231]
	v_pk_mul_f32 v[126:127], v[126:127], v[232:233]
	v_mul_f32_e32 v246, v96, v96
	v_mul_f32_e32 v247, v97, v97
	v_mul_f32_e32 v248, v98, v98
	v_mul_f32_e32 v249, v99, v99
	v_fmac_f32_e32 v246, v100, v100
	v_fmac_f32_e32 v247, v101, v101
	v_fmac_f32_e32 v248, v102, v102
	v_fmac_f32_e32 v249, v103, v103
	v_fmac_f32_e32 v246, v104, v104
	v_fmac_f32_e32 v247, v105, v105
	v_fmac_f32_e32 v248, v106, v106
	v_fmac_f32_e32 v249, v107, v107
	v_fmac_f32_e32 v246, v108, v108
	v_fmac_f32_e32 v247, v109, v109
	v_fmac_f32_e32 v248, v110, v110
	v_fmac_f32_e32 v249, v111, v111
	v_fmac_f32_e32 v246, v112, v112
	v_fmac_f32_e32 v247, v113, v113
	v_fmac_f32_e32 v248, v114, v114
	v_fmac_f32_e32 v249, v115, v115
	v_fmac_f32_e32 v246, v116, v116
	v_fmac_f32_e32 v247, v117, v117
	v_fmac_f32_e32 v248, v118, v118
	v_fmac_f32_e32 v249, v119, v119
	v_fmac_f32_e32 v246, v120, v120
	v_fmac_f32_e32 v247, v121, v121
	v_fmac_f32_e32 v248, v122, v122
	v_fmac_f32_e32 v249, v123, v123
	v_fmac_f32_e32 v246, v124, v124
	v_fmac_f32_e32 v247, v125, v125
	v_fmac_f32_e32 v248, v126, v126
	v_fmac_f32_e32 v249, v127, v127
	v_add_f32_dpp v246, v246, v246 quad_perm:[1,0,3,2] row_mask:0xf bank_mask:0xf
	v_add_f32_dpp v247, v247, v247 quad_perm:[1,0,3,2] row_mask:0xf bank_mask:0xf
	v_add_f32_dpp v248, v248, v248 quad_perm:[1,0,3,2] row_mask:0xf bank_mask:0xf
	v_add_f32_dpp v249, v249, v249 quad_perm:[1,0,3,2] row_mask:0xf bank_mask:0xf
	v_add_f32_dpp v246, v246, v246 quad_perm:[2,3,0,1] row_mask:0xf bank_mask:0xf
	v_add_f32_dpp v247, v247, v247 quad_perm:[2,3,0,1] row_mask:0xf bank_mask:0xf
	v_add_f32_dpp v248, v248, v248 quad_perm:[2,3,0,1] row_mask:0xf bank_mask:0xf
	v_add_f32_dpp v249, v249, v249 quad_perm:[2,3,0,1] row_mask:0xf bank_mask:0xf
	v_add_f32_dpp v246, v246, v246 row_half_mirror row_mask:0xf bank_mask:0xf
	v_add_f32_dpp v247, v247, v247 row_half_mirror row_mask:0xf bank_mask:0xf
	v_add_f32_dpp v248, v248, v248 row_half_mirror row_mask:0xf bank_mask:0xf
	v_add_f32_dpp v249, v249, v249 row_half_mirror row_mask:0xf bank_mask:0xf
	v_add_f32_dpp v246, v246, v246 row_mirror row_mask:0xf bank_mask:0xf
	v_add_f32_dpp v247, v247, v247 row_mirror row_mask:0xf bank_mask:0xf
	v_add_f32_dpp v248, v248, v248 row_mirror row_mask:0xf bank_mask:0xf
	v_add_f32_dpp v249, v249, v249 row_mirror row_mask:0xf bank_mask:0xf
	global_store_dword v[242:243], v246, off offset:2048
	global_store_dword v[242:243], v247, off offset:2176
	global_store_dword v[242:243], v248, off offset:2304
	global_store_dword v[242:243], v249, off offset:2432
	ds_write2_b32 v200, v96, v97 offset0:0 offset1:132
	ds_write2_b32 v201, v98, v99 offset0:0 offset1:132
	ds_write2_b32 v200, v100, v101 offset0:16 offset1:148
	ds_write2_b32 v201, v102, v103 offset0:16 offset1:148
	ds_write2_b32 v200, v104, v105 offset0:32 offset1:164
	ds_write2_b32 v201, v106, v107 offset0:32 offset1:164
	ds_write2_b32 v200, v108, v109 offset0:48 offset1:180
	ds_write2_b32 v201, v110, v111 offset0:48 offset1:180
	ds_write2_b32 v200, v112, v113 offset0:64 offset1:196
	ds_write2_b32 v201, v114, v115 offset0:64 offset1:196
	ds_write2_b32 v200, v116, v117 offset0:80 offset1:212
	ds_write2_b32 v201, v118, v119 offset0:80 offset1:212
	ds_write2_b32 v200, v120, v121 offset0:96 offset1:228
	ds_write2_b32 v201, v122, v123 offset0:96 offset1:228
	ds_write2_b32 v200, v124, v125 offset0:112 offset1:244
	ds_write2_b32 v201, v126, v127 offset0:112 offset1:244
	v_lshl_add_u64 v[242:243], v[242:243], 0, v[244:245]
	s_waitcnt lgkmcnt(0)
	ds_read_b128 v[64:67], v202
	ds_read_b128 v[68:71], v202 offset:1056
	ds_read_b128 v[72:75], v202 offset:2112
	ds_read_b128 v[76:79], v202 offset:3168
	ds_read_b128 v[80:83], v202 offset:4224
	ds_read_b128 v[84:87], v202 offset:5280
	ds_read_b128 v[88:91], v202 offset:6336
	ds_read_b128 v[92:95], v202 offset:7392
	ds_read_b128 v[96:99], v202 offset:8448
	s_waitcnt lgkmcnt(8)
	v_lshl_add_u64 v[206:207], v[204:205], 0, s[8:9]
	v_cvt_pk_bf16_f32 v64, v64, v65
	v_cvt_pk_bf16_f32 v65, v66, v67
	s_add_u32 s8, s8, s4
	s_addc_u32 s9, s9, 0
	global_store_dwordx2 v[206:207], v[64:65], off
	ds_read_b128 v[100:103], v202 offset:9504
	s_waitcnt lgkmcnt(8)
; DI float shx(float v, int mask, int lane) { return __int_as_float(__builtin_amdgcn_ds_bpermute((lane ^ mask) << 2, __float_as_int(v))); }
; DI void epi_slab(const GemmCfg c, const f32x16 (&acc)[4], float* sW, const float* rss, const size_t row0, const int g, const int lane,
;                  float* const g_h, u16* const g_hb, float* const g_out, const int final_out) {
;     ...
;       } else if (c.epi == EPI_QABS) {
;         f32x4 x = v * rs;
;         float s = x[0] * x[0] + x[1] * x[1] + x[2] * x[2] + x[3] * x[3];
;         s += shx(s, 1, ln_); s += shx(s, 2, ln_); s += shx(s, 4, ln_); s += shx(s, 8, ln_); s += shx(s, 16, ln_);
;         if (l31 == 0) c.f0[row * 32 + g] = s;
;         *(u32x2*)(c.o16 + row * 4096 + col) = MK2(pack2(x[0], x[1]), pack2(x[2], x[3]));
	v_lshl_add_u64 v[206:207], v[204:205], 0, s[8:9]
	v_cvt_pk_bf16_f32 v68, v68, v69
	v_cvt_pk_bf16_f32 v69, v70, v71
	s_add_u32 s8, s8, s4
	s_addc_u32 s9, s9, 0
	global_store_dwordx2 v[206:207], v[68:69], off
	ds_read_b128 v[104:107], v202 offset:10560
	s_waitcnt lgkmcnt(8)
	v_lshl_add_u64 v[206:207], v[204:205], 0, s[8:9]
	v_cvt_pk_bf16_f32 v72, v72, v73
	v_cvt_pk_bf16_f32 v73, v74, v75
	s_add_u32 s8, s8, s4
	s_addc_u32 s9, s9, 0
	global_store_dwordx2 v[206:207], v[72:73], off
	ds_read_b128 v[108:111], v202 offset:11616
	s_waitcnt lgkmcnt(8)
	v_lshl_add_u64 v[206:207], v[204:205], 0, s[8:9]
	v_cvt_pk_bf16_f32 v76, v76, v77
	v_cvt_pk_bf16_f32 v77, v78, v79
	s_add_u32 s8, s8, s4
	s_addc_u32 s9, s9, 0
	global_store_dwordx2 v[206:207], v[76:77], off
	ds_read_b128 v[112:115], v202 offset:12672
	s_waitcnt lgkmcnt(8)
	v_lshl_add_u64 v[206:207], v[204:205], 0, s[8:9]
	v_cvt_pk_bf16_f32 v80, v80, v81
	v_cvt_pk_bf16_f32 v81, v82, v83
	s_add_u32 s8, s8, s4
	s_addc_u32 s9, s9, 0
	global_store_dwordx2 v[206:207], v[80:81], off
	ds_read_b128 v[116:119], v202 offset:13728
	s_waitcnt lgkmcnt(8)
	v_lshl_add_u64 v[206:207], v[204:205], 0, s[8:9]
	v_cvt_pk_bf16_f32 v84, v84, v85
	v_cvt_pk_bf16_f32 v85, v86, v87
	s_add_u32 s8, s8, s4
	s_addc_u32 s9, s9, 0
	global_store_dwordx2 v[206:207], v[84:85], off
	ds_read_b128 v[120:123], v202 offset:14784
	s_waitcnt lgkmcnt(8)
	v_lshl_add_u64 v[206:207], v[204:205], 0, s[8:9]
	v_cvt_pk_bf16_f32 v88, v88, v89
	v_cvt_pk_bf16_f32 v89, v90, v91
	s_add_u32 s8, s8, s4
	s_addc_u32 s9, s9, 0
	global_store_dwordx2 v[206:207], v[88:89], off
	ds_read_b128 v[124:127], v202 offset:15840
	s_waitcnt lgkmcnt(8)
	v_lshl_add_u64 v[206:207], v[204:205], 0, s[8:9]
	v_cvt_pk_bf16_f32 v92, v92, v93
	v_cvt_pk_bf16_f32 v93, v94, v95
	s_add_u32 s8, s8, s4
	s_addc_u32 s9, s9, 0
	global_store_dwordx2 v[206:207], v[92:93], off
	s_waitcnt lgkmcnt(7)
	v_lshl_add_u64 v[206:207], v[204:205], 0, s[8:9]
	v_cvt_pk_bf16_f32 v96, v96, v97
	v_cvt_pk_bf16_f32 v97, v98, v99
	s_add_u32 s8, s8, s4
	s_addc_u32 s9, s9, 0
	global_store_dwordx2 v[206:207], v[96:97], off
	s_waitcnt lgkmcnt(6)
	v_lshl_add_u64 v[206:207], v[204:205], 0, s[8:9]
	v_cvt_pk_bf16_f32 v100, v100, v101
	v_cvt_pk_bf16_f32 v101, v102, v103
	s_add_u32 s8, s8, s4
	s_addc_u32 s9, s9, 0
	global_store_dwordx2 v[206:207], v[100:101], off
	s_waitcnt lgkmcnt(5)
	v_lshl_add_u64 v[206:207], v[204:205], 0, s[8:9]
	v_cvt_pk_bf16_f32 v104, v104, v105
	v_cvt_pk_bf16_f32 v105, v106, v107
	s_add_u32 s8, s8, s4
	s_addc_u32 s9, s9, 0
	global_store_dwordx2 v[206:207], v[104:105], off
	s_waitcnt lgkmcnt(4)
	v_lshl_add_u64 v[206:207], v[204:205], 0, s[8:9]
	v_cvt_pk_bf16_f32 v108, v108, v109
	v_cvt_pk_bf16_f32 v109, v110, v111
	s_add_u32 s8, s8, s4
	s_addc_u32 s9, s9, 0
	global_store_dwordx2 v[206:207], v[108:109], off
	s_waitcnt lgkmcnt(3)
	v_lshl_add_u64 v[206:207], v[204:205], 0, s[8:9]
	v_cvt_pk_bf16_f32 v112, v112, v113
	v_cvt_pk_bf16_f32 v113, v114, v115
	s_add_u32 s8, s8, s4
	s_addc_u32 s9, s9, 0
	global_store_dwordx2 v[206:207], v[112:113], off
	s_waitcnt lgkmcnt(2)
	v_lshl_add_u64 v[206:207], v[204:205], 0, s[8:9]
	v_cvt_pk_bf16_f32 v116, v116, v117
	v_cvt_pk_bf16_f32 v117, v118, v119
	s_add_u32 s8, s8, s4
	s_addc_u32 s9, s9, 0
	global_store_dwordx2 v[206:207], v[116:117], off
	s_waitcnt lgkmcnt(1)
	v_lshl_add_u64 v[206:207], v[204:205], 0, s[8:9]
	v_cvt_pk_bf16_f32 v120, v120, v121
	v_cvt_pk_bf16_f32 v121, v122, v123
	s_add_u32 s8, s8, s4
	s_addc_u32 s9, s9, 0
	global_store_dwordx2 v[206:207], v[120:121], off
	s_waitcnt lgkmcnt(0)
	v_lshl_add_u64 v[206:207], v[204:205], 0, s[8:9]
	v_cvt_pk_bf16_f32 v124, v124, v125
	v_cvt_pk_bf16_f32 v125, v126, v127
	s_add_u32 s8, s8, s4
	s_addc_u32 s9, s9, 0
	global_store_dwordx2 v[206:207], v[124:125], off
	v_pk_mul_f32 v[0:1], v[0:1], v[234:235]
	v_pk_mul_f32 v[2:3], v[2:3], v[236:237]
	v_pk_mul_f32 v[4:5], v[4:5], v[234:235]
	v_pk_mul_f32 v[6:7], v[6:7], v[236:237]
	v_pk_mul_f32 v[8:9], v[8:9], v[234:235]
	v_pk_mul_f32 v[10:11], v[10:11], v[236:237]
	v_pk_mul_f32 v[12:13], v[12:13], v[234:235]
	v_pk_mul_f32 v[14:15], v[14:15], v[236:237]
	v_pk_mul_f32 v[16:17], v[16:17], v[234:235]
	v_pk_mul_f32 v[18:19], v[18:19], v[236:237]
	v_pk_mul_f32 v[20:21], v[20:21], v[234:235]
	v_pk_mul_f32 v[22:23], v[22:23], v[236:237]
	v_pk_mul_f32 v[24:25], v[24:25], v[234:235]
	v_pk_mul_f32 v[26:27], v[26:27], v[236:237]
	v_pk_mul_f32 v[28:29], v[28:29], v[234:235]
	v_pk_mul_f32 v[30:31], v[30:31], v[236:237]
	v_mul_f32_e32 v246, v0, v0
	v_mul_f32_e32 v247, v1, v1
	v_mul_f32_e32 v248, v2, v2
	v_mul_f32_e32 v249, v3, v3
	v_fmac_f32_e32 v246, v4, v4
	v_fmac_f32_e32 v247, v5, v5
	v_fmac_f32_e32 v248, v6, v6
	v_fmac_f32_e32 v249, v7, v7
	v_fmac_f32_e32 v246, v8, v8
	v_fmac_f32_e32 v247, v9, v9
	v_fmac_f32_e32 v248, v10, v10
	v_fmac_f32_e32 v249, v11, v11
	v_fmac_f32_e32 v246, v12, v12
	v_fmac_f32_e32 v247, v13, v13
	v_fmac_f32_e32 v248, v14, v14
	v_fmac_f32_e32 v249, v15, v15
	v_fmac_f32_e32 v246, v16, v16
	v_fmac_f32_e32 v247, v17, v17
	v_fmac_f32_e32 v248, v18, v18
	v_fmac_f32_e32 v249, v19, v19
	v_fmac_f32_e32 v246, v20, v20
	v_fmac_f32_e32 v247, v21, v21
	v_fmac_f32_e32 v248, v22, v22
	v_fmac_f32_e32 v249, v23, v23
	v_fmac_f32_e32 v246, v24, v24
	v_fmac_f32_e32 v247, v25, v25
	v_fmac_f32_e32 v248, v26, v26
	v_fmac_f32_e32 v249, v27, v27
	v_fmac_f32_e32 v246, v28, v28
	v_fmac_f32_e32 v247, v29, v29
	v_fmac_f32_e32 v248, v30, v30
	v_fmac_f32_e32 v249, v31, v31
	v_add_f32_dpp v246, v246, v246 quad_perm:[1,0,3,2] row_mask:0xf bank_mask:0xf
	v_add_f32_dpp v247, v247, v247 quad_perm:[1,0,3,2] row_mask:0xf bank_mask:0xf
	v_add_f32_dpp v248, v248, v248 quad_perm:[1,0,3,2] row_mask:0xf bank_mask:0xf
; DI float shx(float v, int mask, int lane) { return __int_as_float(__builtin_amdgcn_ds_bpermute((lane ^ mask) << 2, __float_as_int(v))); }
; DI int crow(int i, int hh) { return (i & 3) + 8 * (i >> 2) + 4 * hh; }
; DI void epi_slab(const GemmCfg c, const f32x16 (&acc)[4], float* sW, const float* rss, const size_t row0, const int g, const int lane,
;                  float* const g_h, u16* const g_hb, float* const g_out, const int final_out) {
;     ...
;   for (int nb = 0; nb < 4; ++nb)
; #pragma unroll
;     for (int i = 0; i < 16; ++i) sW[crow(i, hh) * 132 + nb * 32 + l31] = acc[nb][i];
;     ...
;       } else if (c.epi == EPI_QABS) {
;         f32x4 x = v * rs;
;         float s = x[0] * x[0] + x[1] * x[1] + x[2] * x[2] + x[3] * x[3];
;         s += shx(s, 1, ln_); s += shx(s, 2, ln_); s += shx(s, 4, ln_); s += shx(s, 8, ln_); s += shx(s, 16, ln_);
;         if (l31 == 0) c.f0[row * 32 + g] = s;
;         *(u32x2*)(c.o16 + row * 4096 + col) = MK2(pack2(x[0], x[1]), pack2(x[2], x[3]));
	v_add_f32_dpp v249, v249, v249 quad_perm:[1,0,3,2] row_mask:0xf bank_mask:0xf
	v_add_f32_dpp v246, v246, v246 quad_perm:[2,3,0,1] row_mask:0xf bank_mask:0xf
	v_add_f32_dpp v247, v247, v247 quad_perm:[2,3,0,1] row_mask:0xf bank_mask:0xf
	v_add_f32_dpp v248, v248, v248 quad_perm:[2,3,0,1] row_mask:0xf bank_mask:0xf
	v_add_f32_dpp v249, v249, v249 quad_perm:[2,3,0,1] row_mask:0xf bank_mask:0xf
	v_add_f32_dpp v246, v246, v246 row_half_mirror row_mask:0xf bank_mask:0xf
	v_add_f32_dpp v247, v247, v247 row_half_mirror row_mask:0xf bank_mask:0xf
	v_add_f32_dpp v248, v248, v248 row_half_mirror row_mask:0xf bank_mask:0xf
	v_add_f32_dpp v249, v249, v249 row_half_mirror row_mask:0xf bank_mask:0xf
	v_add_f32_dpp v246, v246, v246 row_mirror row_mask:0xf bank_mask:0xf
	v_add_f32_dpp v247, v247, v247 row_mirror row_mask:0xf bank_mask:0xf
	v_add_f32_dpp v248, v248, v248 row_mirror row_mask:0xf bank_mask:0xf
	v_add_f32_dpp v249, v249, v249 row_mirror row_mask:0xf bank_mask:0xf
	global_store_dword v[242:243], v246, off offset:0
	global_store_dword v[242:243], v247, off offset:128
	global_store_dword v[242:243], v248, off offset:256
	global_store_dword v[242:243], v249, off offset:384
	ds_write2_b32 v198, v0, v1 offset0:0 offset1:132
	ds_write2_b32 v199, v2, v3 offset0:0 offset1:132
	ds_write2_b32 v198, v4, v5 offset0:16 offset1:148
	ds_write2_b32 v199, v6, v7 offset0:16 offset1:148
	ds_write2_b32 v198, v8, v9 offset0:32 offset1:164
	ds_write2_b32 v199, v10, v11 offset0:32 offset1:164
	ds_write2_b32 v198, v12, v13 offset0:48 offset1:180
	ds_write2_b32 v199, v14, v15 offset0:48 offset1:180
	ds_write2_b32 v198, v16, v17 offset0:64 offset1:196
	ds_write2_b32 v199, v18, v19 offset0:64 offset1:196
	ds_write2_b32 v198, v20, v21 offset0:80 offset1:212
	ds_write2_b32 v199, v22, v23 offset0:80 offset1:212
	ds_write2_b32 v198, v24, v25 offset0:96 offset1:228
	ds_write2_b32 v199, v26, v27 offset0:96 offset1:228
	ds_write2_b32 v198, v28, v29 offset0:112 offset1:244
	ds_write2_b32 v199, v30, v31 offset0:112 offset1:244
	v_pk_mul_f32 v[32:33], v[32:33], v[238:239]
	v_pk_mul_f32 v[34:35], v[34:35], v[240:241]
	v_pk_mul_f32 v[36:37], v[36:37], v[238:239]
	v_pk_mul_f32 v[38:39], v[38:39], v[240:241]
	v_pk_mul_f32 v[40:41], v[40:41], v[238:239]
	v_pk_mul_f32 v[42:43], v[42:43], v[240:241]
	v_pk_mul_f32 v[44:45], v[44:45], v[238:239]
	v_pk_mul_f32 v[46:47], v[46:47], v[240:241]
	v_pk_mul_f32 v[48:49], v[48:49], v[238:239]
	v_pk_mul_f32 v[50:51], v[50:51], v[240:241]
	v_pk_mul_f32 v[52:53], v[52:53], v[238:239]
	v_pk_mul_f32 v[54:55], v[54:55], v[240:241]
	v_pk_mul_f32 v[56:57], v[56:57], v[238:239]
	v_pk_mul_f32 v[58:59], v[58:59], v[240:241]
	v_pk_mul_f32 v[60:61], v[60:61], v[238:239]
	v_pk_mul_f32 v[62:63], v[62:63], v[240:241]
	v_mul_f32_e32 v246, v32, v32
	v_mul_f32_e32 v247, v33, v33
	v_mul_f32_e32 v248, v34, v34
	v_mul_f32_e32 v249, v35, v35
	v_fmac_f32_e32 v246, v36, v36
	v_fmac_f32_e32 v247, v37, v37
	v_fmac_f32_e32 v248, v38, v38
	v_fmac_f32_e32 v249, v39, v39
	v_fmac_f32_e32 v246, v40, v40
	v_fmac_f32_e32 v247, v41, v41
	v_fmac_f32_e32 v248, v42, v42
	v_fmac_f32_e32 v249, v43, v43
	v_fmac_f32_e32 v246, v44, v44
	v_fmac_f32_e32 v247, v45, v45
	v_fmac_f32_e32 v248, v46, v46
	v_fmac_f32_e32 v249, v47, v47
	v_fmac_f32_e32 v246, v48, v48
	v_fmac_f32_e32 v247, v49, v49
	v_fmac_f32_e32 v248, v50, v50
	v_fmac_f32_e32 v249, v51, v51
	v_fmac_f32_e32 v246, v52, v52
	v_fmac_f32_e32 v247, v53, v53
	v_fmac_f32_e32 v248, v54, v54
	v_fmac_f32_e32 v249, v55, v55
	v_fmac_f32_e32 v246, v56, v56
	v_fmac_f32_e32 v247, v57, v57
	v_fmac_f32_e32 v248, v58, v58
	v_fmac_f32_e32 v249, v59, v59
	v_fmac_f32_e32 v246, v60, v60
	v_fmac_f32_e32 v247, v61, v61
	v_fmac_f32_e32 v248, v62, v62
	v_fmac_f32_e32 v249, v63, v63
	v_add_f32_dpp v246, v246, v246 quad_perm:[1,0,3,2] row_mask:0xf bank_mask:0xf
	v_add_f32_dpp v247, v247, v247 quad_perm:[1,0,3,2] row_mask:0xf bank_mask:0xf
	v_add_f32_dpp v248, v248, v248 quad_perm:[1,0,3,2] row_mask:0xf bank_mask:0xf
	v_add_f32_dpp v249, v249, v249 quad_perm:[1,0,3,2] row_mask:0xf bank_mask:0xf
	v_add_f32_dpp v246, v246, v246 quad_perm:[2,3,0,1] row_mask:0xf bank_mask:0xf
	v_add_f32_dpp v247, v247, v247 quad_perm:[2,3,0,1] row_mask:0xf bank_mask:0xf
	v_add_f32_dpp v248, v248, v248 quad_perm:[2,3,0,1] row_mask:0xf bank_mask:0xf
	v_add_f32_dpp v249, v249, v249 quad_perm:[2,3,0,1] row_mask:0xf bank_mask:0xf
	v_add_f32_dpp v246, v246, v246 row_half_mirror row_mask:0xf bank_mask:0xf
	v_add_f32_dpp v247, v247, v247 row_half_mirror row_mask:0xf bank_mask:0xf
	v_add_f32_dpp v248, v248, v248 row_half_mirror row_mask:0xf bank_mask:0xf
	v_add_f32_dpp v249, v249, v249 row_half_mirror row_mask:0xf bank_mask:0xf
	v_add_f32_dpp v246, v246, v246 row_mirror row_mask:0xf bank_mask:0xf
	v_add_f32_dpp v247, v247, v247 row_mirror row_mask:0xf bank_mask:0xf
	v_add_f32_dpp v248, v248, v248 row_mirror row_mask:0xf bank_mask:0xf
	v_add_f32_dpp v249, v249, v249 row_mirror row_mask:0xf bank_mask:0xf
	global_store_dword v[242:243], v246, off offset:2048
	global_store_dword v[242:243], v247, off offset:2176
	global_store_dword v[242:243], v248, off offset:2304
	global_store_dword v[242:243], v249, off offset:2432
	ds_write2_b32 v200, v32, v33 offset0:0 offset1:132
	ds_write2_b32 v201, v34, v35 offset0:0 offset1:132
	ds_write2_b32 v200, v36, v37 offset0:16 offset1:148
	ds_write2_b32 v201, v38, v39 offset0:16 offset1:148
	ds_write2_b32 v200, v40, v41 offset0:32 offset1:164
	ds_write2_b32 v201, v42, v43 offset0:32 offset1:164
	ds_write2_b32 v200, v44, v45 offset0:48 offset1:180
	ds_write2_b32 v201, v46, v47 offset0:48 offset1:180
	ds_write2_b32 v200, v48, v49 offset0:64 offset1:196
	ds_write2_b32 v201, v50, v51 offset0:64 offset1:196
	ds_write2_b32 v200, v52, v53 offset0:80 offset1:212
	ds_write2_b32 v201, v54, v55 offset0:80 offset1:212
	ds_write2_b32 v200, v56, v57 offset0:96 offset1:228
	ds_write2_b32 v201, v58, v59 offset0:96 offset1:228
	ds_write2_b32 v200, v60, v61 offset0:112 offset1:244
	ds_write2_b32 v201, v62, v63 offset0:112 offset1:244
	s_waitcnt lgkmcnt(0)
; DI float shx(float v, int mask, int lane) { return __int_as_float(__builtin_amdgcn_ds_bpermute((lane ^ mask) << 2, __float_as_int(v))); }
; DI void epi_slab(const GemmCfg c, const f32x16 (&acc)[4], float* sW, const float* rss, const size_t row0, const int g, const int lane,
;                  float* const g_h, u16* const g_hb, float* const g_out, const int final_out) {
;     ...
; #pragma unroll 2
;     for (int it = 0; it < 16; ++it) {
;       const int r = hh + 2 * it;
;       const size_t row = row0 + r;
;       f32x4 v = *(const f32x4*)(sW + r * 132 + c4);
;       const float rs = c.use_rs ? rsqrtf(rss[r] * invK + 1e-6f) : 1.f;
;     ...
;       } else if (c.epi == EPI_QABS) {
;         f32x4 x = v * rs;
;         float s = x[0] * x[0] + x[1] * x[1] + x[2] * x[2] + x[3] * x[3];
;         s += shx(s, 1, ln_); s += shx(s, 2, ln_); s += shx(s, 4, ln_); s += shx(s, 8, ln_); s += shx(s, 16, ln_);
;         if (l31 == 0) c.f0[row * 32 + g] = s;
;         *(u32x2*)(c.o16 + row * 4096 + col) = MK2(pack2(x[0], x[1]), pack2(x[2], x[3]));
	ds_read_b128 v[0:3], v202
	ds_read_b128 v[4:7], v202 offset:1056
	ds_read_b128 v[8:11], v202 offset:2112
	ds_read_b128 v[12:15], v202 offset:3168
	ds_read_b128 v[16:19], v202 offset:4224
	ds_read_b128 v[20:23], v202 offset:5280
	ds_read_b128 v[24:27], v202 offset:6336
	ds_read_b128 v[28:31], v202 offset:7392
	ds_read_b128 v[32:35], v202 offset:8448
	s_waitcnt lgkmcnt(8)
	v_lshl_add_u64 v[206:207], v[204:205], 0, s[8:9]
	v_cvt_pk_bf16_f32 v0, v0, v1
	v_cvt_pk_bf16_f32 v1, v2, v3
	s_add_u32 s8, s8, s4
	s_addc_u32 s9, s9, 0
	global_store_dwordx2 v[206:207], v[0:1], off
	ds_read_b128 v[36:39], v202 offset:9504
	s_waitcnt lgkmcnt(8)
	v_lshl_add_u64 v[206:207], v[204:205], 0, s[8:9]
	v_cvt_pk_bf16_f32 v4, v4, v5
	v_cvt_pk_bf16_f32 v5, v6, v7
	s_add_u32 s8, s8, s4
	s_addc_u32 s9, s9, 0
	global_store_dwordx2 v[206:207], v[4:5], off
	ds_read_b128 v[40:43], v202 offset:10560
	s_waitcnt lgkmcnt(8)
	v_lshl_add_u64 v[206:207], v[204:205], 0, s[8:9]
	v_cvt_pk_bf16_f32 v8, v8, v9
	v_cvt_pk_bf16_f32 v9, v10, v11
	s_add_u32 s8, s8, s4
	s_addc_u32 s9, s9, 0
	global_store_dwordx2 v[206:207], v[8:9], off
	ds_read_b128 v[44:47], v202 offset:11616
	s_waitcnt lgkmcnt(8)
	v_lshl_add_u64 v[206:207], v[204:205], 0, s[8:9]
	v_cvt_pk_bf16_f32 v12, v12, v13
	v_cvt_pk_bf16_f32 v13, v14, v15
	s_add_u32 s8, s8, s4
	s_addc_u32 s9, s9, 0
	global_store_dwordx2 v[206:207], v[12:13], off
	ds_read_b128 v[48:51], v202 offset:12672
	s_waitcnt lgkmcnt(8)
	v_lshl_add_u64 v[206:207], v[204:205], 0, s[8:9]
	v_cvt_pk_bf16_f32 v16, v16, v17
	v_cvt_pk_bf16_f32 v17, v18, v19
	s_add_u32 s8, s8, s4
	s_addc_u32 s9, s9, 0
	global_store_dwordx2 v[206:207], v[16:17], off
	ds_read_b128 v[52:55], v202 offset:13728
	s_waitcnt lgkmcnt(8)
	v_lshl_add_u64 v[206:207], v[204:205], 0, s[8:9]
	v_cvt_pk_bf16_f32 v20, v20, v21
	v_cvt_pk_bf16_f32 v21, v22, v23
	s_add_u32 s8, s8, s4
	s_addc_u32 s9, s9, 0
	global_store_dwordx2 v[206:207], v[20:21], off
	ds_read_b128 v[56:59], v202 offset:14784
	s_waitcnt lgkmcnt(8)
	v_lshl_add_u64 v[206:207], v[204:205], 0, s[8:9]
	v_cvt_pk_bf16_f32 v24, v24, v25
	v_cvt_pk_bf16_f32 v25, v26, v27
	s_add_u32 s8, s8, s4
	s_addc_u32 s9, s9, 0
	global_store_dwordx2 v[206:207], v[24:25], off
	ds_read_b128 v[60:63], v202 offset:15840
	s_waitcnt lgkmcnt(8)
	v_lshl_add_u64 v[206:207], v[204:205], 0, s[8:9]
	v_cvt_pk_bf16_f32 v28, v28, v29
	v_cvt_pk_bf16_f32 v29, v30, v31
	s_add_u32 s8, s8, s4
	s_addc_u32 s9, s9, 0
	global_store_dwordx2 v[206:207], v[28:29], off
	s_waitcnt lgkmcnt(7)
	v_lshl_add_u64 v[206:207], v[204:205], 0, s[8:9]
	v_cvt_pk_bf16_f32 v32, v32, v33
	v_cvt_pk_bf16_f32 v33, v34, v35
	s_add_u32 s8, s8, s4
	s_addc_u32 s9, s9, 0
	global_store_dwordx2 v[206:207], v[32:33], off
	s_waitcnt lgkmcnt(6)
	v_lshl_add_u64 v[206:207], v[204:205], 0, s[8:9]
	v_cvt_pk_bf16_f32 v36, v36, v37
	v_cvt_pk_bf16_f32 v37, v38, v39
	s_add_u32 s8, s8, s4
	s_addc_u32 s9, s9, 0
	global_store_dwordx2 v[206:207], v[36:37], off
	s_waitcnt lgkmcnt(5)
	v_lshl_add_u64 v[206:207], v[204:205], 0, s[8:9]
	v_cvt_pk_bf16_f32 v40, v40, v41
	v_cvt_pk_bf16_f32 v41, v42, v43
	s_add_u32 s8, s8, s4
	s_addc_u32 s9, s9, 0
	global_store_dwordx2 v[206:207], v[40:41], off
	s_waitcnt lgkmcnt(4)
	v_lshl_add_u64 v[206:207], v[204:205], 0, s[8:9]
	v_cvt_pk_bf16_f32 v44, v44, v45
	v_cvt_pk_bf16_f32 v45, v46, v47
	s_add_u32 s8, s8, s4
	s_addc_u32 s9, s9, 0
	global_store_dwordx2 v[206:207], v[44:45], off
	s_waitcnt lgkmcnt(3)
	v_lshl_add_u64 v[206:207], v[204:205], 0, s[8:9]
	v_cvt_pk_bf16_f32 v48, v48, v49
	v_cvt_pk_bf16_f32 v49, v50, v51
	s_add_u32 s8, s8, s4
	s_addc_u32 s9, s9, 0
	global_store_dwordx2 v[206:207], v[48:49], off
	s_waitcnt lgkmcnt(2)
	v_lshl_add_u64 v[206:207], v[204:205], 0, s[8:9]
	v_cvt_pk_bf16_f32 v52, v52, v53
	v_cvt_pk_bf16_f32 v53, v54, v55
	s_add_u32 s8, s8, s4
	s_addc_u32 s9, s9, 0
	global_store_dwordx2 v[206:207], v[52:53], off
	s_waitcnt lgkmcnt(1)
	v_lshl_add_u64 v[206:207], v[204:205], 0, s[8:9]
	v_cvt_pk_bf16_f32 v56, v56, v57
	v_cvt_pk_bf16_f32 v57, v58, v59
	s_add_u32 s8, s8, s4
	s_addc_u32 s9, s9, 0
	global_store_dwordx2 v[206:207], v[56:57], off
	s_waitcnt lgkmcnt(0)
	v_lshl_add_u64 v[206:207], v[204:205], 0, s[8:9]
	v_cvt_pk_bf16_f32 v60, v60, v61
	v_cvt_pk_bf16_f32 v61, v62, v63
	s_add_u32 s8, s8, s4
	s_addc_u32 s9, s9, 0
	global_store_dwordx2 v[206:207], v[60:61], off
	s_branch .LBB0_108
; DI void epi_slab(const GemmCfg c, const f32x16 (&acc)[4], float* sW, const float* rss, const size_t row0, const int g, const int lane,
;                  float* const g_h, u16* const g_hb, float* const g_out, const int final_out) {
;     ...
; #pragma unroll 2
;     for (int it = 0; it < 16; ++it) {
;       const int r = hh + 2 * it;
;       const size_t row = row0 + r;
;       f32x4 v = *(const f32x4*)(sW + r * 132 + c4);
;       const float rs = c.use_rs ? rsqrtf(rss[r] * invK + 1e-6f) : 1.f;
;     ...
;       } else if (c.epi == EPI_QIDX) {
;         f32x4 x = v * (rs * 0.125f);
;         *(u32x2*)(c.o16 + row * 512 + col) = MK2(pack2(x[0], x[1]), pack2(x[2], x[3]));
.Lqidx2:
	v_and_b32_e32 v222, 15, v185
	v_lshrrev_b32_e32 v223, 4, v185
	s_lshl_b32 s4, s86, 2
	s_add_i32 s4, s4, 0x24000
	v_lshl_add_u32 v224, v223, 4, s4
	ds_read_b128 v[226:229], v224
	ds_read_b128 v[230:233], v224 offset:64
	ds_read_b128 v[234:237], v224 offset:128
	ds_read_b128 v[238:241], v224 offset:192
	v_mul_u32_u24_e32 v198, 0x840, v223
	v_lshl_add_u32 v198, v222, 2, v198
	v_add_u32_e32 v198, s53, v198
	v_add_u32_e32 v199, 0x420, v198
	v_add_u32_e32 v200, 0x2100, v198
	v_add_u32_e32 v201, 0x2520, v198
	v_lshrrev_b32_e32 v202, 5, v185
	v_and_b32_e32 v206, 31, v185
	v_mul_u32_u24_e32 v204, 0x210, v202
	v_lshl_add_u32 v204, v206, 4, v204
	v_add_u32_e32 v250, s53, v204
	v_add_u32_e32 v204, s6, v202
	v_lshlrev_b32_e32 v204, 10, v204
	v_lshl_add_u32 v206, v206, 2, s64
	v_lshl_add_u32 v204, v206, 1, v204
	v_mov_b32_e32 v205, 0
	v_lshl_add_u64 v[204:205], v[204:205], 0, s[56:57]
	v_mov_b32_e32 v202, v250
	v_mov_b32_e32 v250, 0x3c800000
	s_movk_i32 s4, 0x800
	s_mov_b64 s[8:9], 0
	s_waitcnt lgkmcnt(0)
	v_fmaak_f32 v226, v191, v226, 0x358637bd
	v_fmaak_f32 v227, v191, v227, 0x358637bd
	v_rsq_f32_e32 v226, v226
	v_rsq_f32_e32 v227, v227
	s_nop 0
	v_mul_f32_e32 v226, 0.125, v226
	v_mul_f32_e32 v227, 0.125, v227
	v_fmaak_f32 v228, v191, v228, 0x358637bd
	v_fmaak_f32 v229, v191, v229, 0x358637bd
	v_rsq_f32_e32 v228, v228
	v_rsq_f32_e32 v229, v229
	s_nop 0
	v_mul_f32_e32 v228, 0.125, v228
	v_mul_f32_e32 v229, 0.125, v229
	v_fmaak_f32 v230, v191, v230, 0x358637bd
	v_fmaak_f32 v231, v191, v231, 0x358637bd
	v_rsq_f32_e32 v230, v230
	v_rsq_f32_e32 v231, v231
	s_nop 0
	v_mul_f32_e32 v230, 0.125, v230
	v_mul_f32_e32 v231, 0.125, v231
	v_fmaak_f32 v232, v191, v232, 0x358637bd
	v_fmaak_f32 v233, v191, v233, 0x358637bd
	v_rsq_f32_e32 v232, v232
	v_rsq_f32_e32 v233, v233
	s_nop 0
	v_mul_f32_e32 v232, 0.125, v232
	v_mul_f32_e32 v233, 0.125, v233
	v_fmaak_f32 v234, v191, v234, 0x358637bd
	v_fmaak_f32 v235, v191, v235, 0x358637bd
	v_rsq_f32_e32 v234, v234
	v_rsq_f32_e32 v235, v235
	s_nop 0
	v_mul_f32_e32 v234, 0.125, v234
	v_mul_f32_e32 v235, 0.125, v235
	v_fmaak_f32 v236, v191, v236, 0x358637bd
	v_fmaak_f32 v237, v191, v237, 0x358637bd
	v_rsq_f32_e32 v236, v236
	v_rsq_f32_e32 v237, v237
	s_nop 0
	v_mul_f32_e32 v236, 0.125, v236
	v_mul_f32_e32 v237, 0.125, v237
	v_fmaak_f32 v238, v191, v238, 0x358637bd
	v_fmaak_f32 v239, v191, v239, 0x358637bd
	v_rsq_f32_e32 v238, v238
	v_rsq_f32_e32 v239, v239
	s_nop 0
	v_mul_f32_e32 v238, 0.125, v238
	v_mul_f32_e32 v239, 0.125, v239
	v_fmaak_f32 v240, v191, v240, 0x358637bd
	v_fmaak_f32 v241, v191, v241, 0x358637bd
	v_rsq_f32_e32 v240, v240
	v_rsq_f32_e32 v241, v241
	s_nop 0
	v_mul_f32_e32 v240, 0.125, v240
	v_mul_f32_e32 v241, 0.125, v241
	v_pk_mul_f32 v[64:65], v[64:65], v[226:227]
	v_pk_mul_f32 v[66:67], v[66:67], v[228:229]
	v_pk_mul_f32 v[68:69], v[68:69], v[226:227]
	v_pk_mul_f32 v[70:71], v[70:71], v[228:229]
	v_pk_mul_f32 v[72:73], v[72:73], v[226:227]
	v_pk_mul_f32 v[74:75], v[74:75], v[228:229]
	v_pk_mul_f32 v[76:77], v[76:77], v[226:227]
	v_pk_mul_f32 v[78:79], v[78:79], v[228:229]
	v_pk_mul_f32 v[80:81], v[80:81], v[226:227]
	v_pk_mul_f32 v[82:83], v[82:83], v[228:229]
	v_pk_mul_f32 v[84:85], v[84:85], v[226:227]
	v_pk_mul_f32 v[86:87], v[86:87], v[228:229]
	v_pk_mul_f32 v[88:89], v[88:89], v[226:227]
	v_pk_mul_f32 v[90:91], v[90:91], v[228:229]
	v_pk_mul_f32 v[92:93], v[92:93], v[226:227]
	v_pk_mul_f32 v[94:95], v[94:95], v[228:229]
	ds_write2_b32 v198, v64, v65 offset0:0 offset1:132
	ds_write2_b32 v199, v66, v67 offset0:0 offset1:132
	ds_write2_b32 v198, v68, v69 offset0:16 offset1:148
	ds_write2_b32 v199, v70, v71 offset0:16 offset1:148
	ds_write2_b32 v198, v72, v73 offset0:32 offset1:164
	ds_write2_b32 v199, v74, v75 offset0:32 offset1:164
	ds_write2_b32 v198, v76, v77 offset0:48 offset1:180
	ds_write2_b32 v199, v78, v79 offset0:48 offset1:180
	ds_write2_b32 v198, v80, v81 offset0:64 offset1:196
	ds_write2_b32 v199, v82, v83 offset0:64 offset1:196
	ds_write2_b32 v198, v84, v85 offset0:80 offset1:212
	ds_write2_b32 v199, v86, v87 offset0:80 offset1:212
	ds_write2_b32 v198, v88, v89 offset0:96 offset1:228
	ds_write2_b32 v199, v90, v91 offset0:96 offset1:228
	ds_write2_b32 v198, v92, v93 offset0:112 offset1:244
	ds_write2_b32 v199, v94, v95 offset0:112 offset1:244
	v_pk_mul_f32 v[96:97], v[96:97], v[230:231]
	v_pk_mul_f32 v[98:99], v[98:99], v[232:233]
	v_pk_mul_f32 v[100:101], v[100:101], v[230:231]
	v_pk_mul_f32 v[102:103], v[102:103], v[232:233]
	v_pk_mul_f32 v[104:105], v[104:105], v[230:231]
	v_pk_mul_f32 v[106:107], v[106:107], v[232:233]
	v_pk_mul_f32 v[108:109], v[108:109], v[230:231]
	v_pk_mul_f32 v[110:111], v[110:111], v[232:233]
	v_pk_mul_f32 v[112:113], v[112:113], v[230:231]
	v_pk_mul_f32 v[114:115], v[114:115], v[232:233]
	v_pk_mul_f32 v[116:117], v[116:117], v[230:231]
	v_pk_mul_f32 v[118:119], v[118:119], v[232:233]
	v_pk_mul_f32 v[120:121], v[120:121], v[230:231]
	v_pk_mul_f32 v[122:123], v[122:123], v[232:233]
	v_pk_mul_f32 v[124:125], v[124:125], v[230:231]
	v_pk_mul_f32 v[126:127], v[126:127], v[232:233]
	ds_write2_b32 v200, v96, v97 offset0:0 offset1:132
	ds_write2_b32 v201, v98, v99 offset0:0 offset1:132
	ds_write2_b32 v200, v100, v101 offset0:16 offset1:148
	ds_write2_b32 v201, v102, v103 offset0:16 offset1:148
	ds_write2_b32 v200, v104, v105 offset0:32 offset1:164
	ds_write2_b32 v201, v106, v107 offset0:32 offset1:164
	ds_write2_b32 v200, v108, v109 offset0:48 offset1:180
	ds_write2_b32 v201, v110, v111 offset0:48 offset1:180
	ds_write2_b32 v200, v112, v113 offset0:64 offset1:196
	ds_write2_b32 v201, v114, v115 offset0:64 offset1:196
	ds_write2_b32 v200, v116, v117 offset0:80 offset1:212
	ds_write2_b32 v201, v118, v119 offset0:80 offset1:212
	ds_write2_b32 v200, v120, v121 offset0:96 offset1:228
	ds_write2_b32 v201, v122, v123 offset0:96 offset1:228
	ds_write2_b32 v200, v124, v125 offset0:112 offset1:244
	ds_write2_b32 v201, v126, v127 offset0:112 offset1:244
	s_waitcnt lgkmcnt(0)
; DI void epi_slab(const GemmCfg c, const f32x16 (&acc)[4], float* sW, const float* rss, const size_t row0, const int g, const int lane,
;                  float* const g_h, u16* const g_hb, float* const g_out, const int final_out) {
;     ...
; #pragma unroll 2
;     for (int it = 0; it < 16; ++it) {
;       const int r = hh + 2 * it;
;       const size_t row = row0 + r;
;       f32x4 v = *(const f32x4*)(sW + r * 132 + c4);
;       const float rs = c.use_rs ? rsqrtf(rss[r] * invK + 1e-6f) : 1.f;
;     ...
;       } else if (c.epi == EPI_QIDX) {
;         f32x4 x = v * (rs * 0.125f);
;         *(u32x2*)(c.o16 + row * 512 + col) = MK2(pack2(x[0], x[1]), pack2(x[2], x[3]));
	ds_read_b128 v[64:67], v202
	ds_read_b128 v[68:71], v202 offset:1056
	ds_read_b128 v[72:75], v202 offset:2112
	ds_read_b128 v[76:79], v202 offset:3168
	ds_read_b128 v[80:83], v202 offset:4224
	ds_read_b128 v[84:87], v202 offset:5280
	ds_read_b128 v[88:91], v202 offset:6336
	ds_read_b128 v[92:95], v202 offset:7392
	ds_read_b128 v[96:99], v202 offset:8448
	s_waitcnt lgkmcnt(8)
	v_lshl_add_u64 v[206:207], v[204:205], 0, s[8:9]
	v_cvt_pk_bf16_f32 v64, v64, v65
	v_cvt_pk_bf16_f32 v65, v66, v67
	s_add_u32 s8, s8, s4
	s_addc_u32 s9, s9, 0
	global_store_dwordx2 v[206:207], v[64:65], off
	ds_read_b128 v[100:103], v202 offset:9504
	s_waitcnt lgkmcnt(8)
	v_lshl_add_u64 v[206:207], v[204:205], 0, s[8:9]
	v_cvt_pk_bf16_f32 v68, v68, v69
	v_cvt_pk_bf16_f32 v69, v70, v71
	s_add_u32 s8, s8, s4
	s_addc_u32 s9, s9, 0
	global_store_dwordx2 v[206:207], v[68:69], off
	ds_read_b128 v[104:107], v202 offset:10560
	s_waitcnt lgkmcnt(8)
	v_lshl_add_u64 v[206:207], v[204:205], 0, s[8:9]
	v_cvt_pk_bf16_f32 v72, v72, v73
	v_cvt_pk_bf16_f32 v73, v74, v75
	s_add_u32 s8, s8, s4
	s_addc_u32 s9, s9, 0
	global_store_dwordx2 v[206:207], v[72:73], off
	ds_read_b128 v[108:111], v202 offset:11616
	s_waitcnt lgkmcnt(8)
	v_lshl_add_u64 v[206:207], v[204:205], 0, s[8:9]
	v_cvt_pk_bf16_f32 v76, v76, v77
	v_cvt_pk_bf16_f32 v77, v78, v79
	s_add_u32 s8, s8, s4
	s_addc_u32 s9, s9, 0
	global_store_dwordx2 v[206:207], v[76:77], off
	ds_read_b128 v[112:115], v202 offset:12672
	s_waitcnt lgkmcnt(8)
	v_lshl_add_u64 v[206:207], v[204:205], 0, s[8:9]
	v_cvt_pk_bf16_f32 v80, v80, v81
	v_cvt_pk_bf16_f32 v81, v82, v83
	s_add_u32 s8, s8, s4
	s_addc_u32 s9, s9, 0
	global_store_dwordx2 v[206:207], v[80:81], off
	ds_read_b128 v[116:119], v202 offset:13728
	s_waitcnt lgkmcnt(8)
	v_lshl_add_u64 v[206:207], v[204:205], 0, s[8:9]
	v_cvt_pk_bf16_f32 v84, v84, v85
	v_cvt_pk_bf16_f32 v85, v86, v87
	s_add_u32 s8, s8, s4
	s_addc_u32 s9, s9, 0
	global_store_dwordx2 v[206:207], v[84:85], off
	ds_read_b128 v[120:123], v202 offset:14784
	s_waitcnt lgkmcnt(8)
	v_lshl_add_u64 v[206:207], v[204:205], 0, s[8:9]
	v_cvt_pk_bf16_f32 v88, v88, v89
	v_cvt_pk_bf16_f32 v89, v90, v91
	s_add_u32 s8, s8, s4
	s_addc_u32 s9, s9, 0
	global_store_dwordx2 v[206:207], v[88:89], off
	ds_read_b128 v[124:127], v202 offset:15840
	s_waitcnt lgkmcnt(8)
	v_lshl_add_u64 v[206:207], v[204:205], 0, s[8:9]
	v_cvt_pk_bf16_f32 v92, v92, v93
	v_cvt_pk_bf16_f32 v93, v94, v95
	s_add_u32 s8, s8, s4
	s_addc_u32 s9, s9, 0
	global_store_dwordx2 v[206:207], v[92:93], off
	s_waitcnt lgkmcnt(7)
	v_lshl_add_u64 v[206:207], v[204:205], 0, s[8:9]
	v_cvt_pk_bf16_f32 v96, v96, v97
	v_cvt_pk_bf16_f32 v97, v98, v99
	s_add_u32 s8, s8, s4
	s_addc_u32 s9, s9, 0
	global_store_dwordx2 v[206:207], v[96:97], off
	s_waitcnt lgkmcnt(6)
	v_lshl_add_u64 v[206:207], v[204:205], 0, s[8:9]
	v_cvt_pk_bf16_f32 v100, v100, v101
	v_cvt_pk_bf16_f32 v101, v102, v103
	s_add_u32 s8, s8, s4
	s_addc_u32 s9, s9, 0
	global_store_dwordx2 v[206:207], v[100:101], off
	s_waitcnt lgkmcnt(5)
	v_lshl_add_u64 v[206:207], v[204:205], 0, s[8:9]
	v_cvt_pk_bf16_f32 v104, v104, v105
	v_cvt_pk_bf16_f32 v105, v106, v107
	s_add_u32 s8, s8, s4
	s_addc_u32 s9, s9, 0
	global_store_dwordx2 v[206:207], v[104:105], off
	s_waitcnt lgkmcnt(4)
	v_lshl_add_u64 v[206:207], v[204:205], 0, s[8:9]
	v_cvt_pk_bf16_f32 v108, v108, v109
	v_cvt_pk_bf16_f32 v109, v110, v111
	s_add_u32 s8, s8, s4
	s_addc_u32 s9, s9, 0
	global_store_dwordx2 v[206:207], v[108:109], off
	s_waitcnt lgkmcnt(3)
	v_lshl_add_u64 v[206:207], v[204:205], 0, s[8:9]
	v_cvt_pk_bf16_f32 v112, v112, v113
	v_cvt_pk_bf16_f32 v113, v114, v115
	s_add_u32 s8, s8, s4
	s_addc_u32 s9, s9, 0
	global_store_dwordx2 v[206:207], v[112:113], off
	s_waitcnt lgkmcnt(2)
	v_lshl_add_u64 v[206:207], v[204:205], 0, s[8:9]
	v_cvt_pk_bf16_f32 v116, v116, v117
	v_cvt_pk_bf16_f32 v117, v118, v119
	s_add_u32 s8, s8, s4
	s_addc_u32 s9, s9, 0
	global_store_dwordx2 v[206:207], v[116:117], off
	s_waitcnt lgkmcnt(1)
	v_lshl_add_u64 v[206:207], v[204:205], 0, s[8:9]
	v_cvt_pk_bf16_f32 v120, v120, v121
	v_cvt_pk_bf16_f32 v121, v122, v123
	s_add_u32 s8, s8, s4
	s_addc_u32 s9, s9, 0
	global_store_dwordx2 v[206:207], v[120:121], off
	s_waitcnt lgkmcnt(0)
	v_lshl_add_u64 v[206:207], v[204:205], 0, s[8:9]
	v_cvt_pk_bf16_f32 v124, v124, v125
	v_cvt_pk_bf16_f32 v125, v126, v127
	s_add_u32 s8, s8, s4
	s_addc_u32 s9, s9, 0
	global_store_dwordx2 v[206:207], v[124:125], off
	v_pk_mul_f32 v[0:1], v[0:1], v[234:235]
	v_pk_mul_f32 v[2:3], v[2:3], v[236:237]
	v_pk_mul_f32 v[4:5], v[4:5], v[234:235]
	v_pk_mul_f32 v[6:7], v[6:7], v[236:237]
	v_pk_mul_f32 v[8:9], v[8:9], v[234:235]
	v_pk_mul_f32 v[10:11], v[10:11], v[236:237]
	v_pk_mul_f32 v[12:13], v[12:13], v[234:235]
	v_pk_mul_f32 v[14:15], v[14:15], v[236:237]
	v_pk_mul_f32 v[16:17], v[16:17], v[234:235]
	v_pk_mul_f32 v[18:19], v[18:19], v[236:237]
	v_pk_mul_f32 v[20:21], v[20:21], v[234:235]
	v_pk_mul_f32 v[22:23], v[22:23], v[236:237]
	v_pk_mul_f32 v[24:25], v[24:25], v[234:235]
	v_pk_mul_f32 v[26:27], v[26:27], v[236:237]
	v_pk_mul_f32 v[28:29], v[28:29], v[234:235]
	v_pk_mul_f32 v[30:31], v[30:31], v[236:237]
	ds_write2_b32 v198, v0, v1 offset0:0 offset1:132
	ds_write2_b32 v199, v2, v3 offset0:0 offset1:132
	ds_write2_b32 v198, v4, v5 offset0:16 offset1:148
	ds_write2_b32 v199, v6, v7 offset0:16 offset1:148
	ds_write2_b32 v198, v8, v9 offset0:32 offset1:164
	ds_write2_b32 v199, v10, v11 offset0:32 offset1:164
	ds_write2_b32 v198, v12, v13 offset0:48 offset1:180
	ds_write2_b32 v199, v14, v15 offset0:48 offset1:180
	ds_write2_b32 v198, v16, v17 offset0:64 offset1:196
	ds_write2_b32 v199, v18, v19 offset0:64 offset1:196
; DI void epi_slab(const GemmCfg c, const f32x16 (&acc)[4], float* sW, const float* rss, const size_t row0, const int g, const int lane,
;                  float* const g_h, u16* const g_hb, float* const g_out, const int final_out) {
;     ...
; #pragma unroll 2
;     for (int it = 0; it < 16; ++it) {
;       const int r = hh + 2 * it;
;       const size_t row = row0 + r;
;       f32x4 v = *(const f32x4*)(sW + r * 132 + c4);
;       const float rs = c.use_rs ? rsqrtf(rss[r] * invK + 1e-6f) : 1.f;
;     ...
;       } else if (c.epi == EPI_QIDX) {
;         f32x4 x = v * (rs * 0.125f);
;         *(u32x2*)(c.o16 + row * 512 + col) = MK2(pack2(x[0], x[1]), pack2(x[2], x[3]));
	ds_write2_b32 v198, v20, v21 offset0:80 offset1:212
	ds_write2_b32 v199, v22, v23 offset0:80 offset1:212
	ds_write2_b32 v198, v24, v25 offset0:96 offset1:228
	ds_write2_b32 v199, v26, v27 offset0:96 offset1:228
	ds_write2_b32 v198, v28, v29 offset0:112 offset1:244
	ds_write2_b32 v199, v30, v31 offset0:112 offset1:244
	v_pk_mul_f32 v[32:33], v[32:33], v[238:239]
	v_pk_mul_f32 v[34:35], v[34:35], v[240:241]
	v_pk_mul_f32 v[36:37], v[36:37], v[238:239]
	v_pk_mul_f32 v[38:39], v[38:39], v[240:241]
	v_pk_mul_f32 v[40:41], v[40:41], v[238:239]
	v_pk_mul_f32 v[42:43], v[42:43], v[240:241]
	v_pk_mul_f32 v[44:45], v[44:45], v[238:239]
	v_pk_mul_f32 v[46:47], v[46:47], v[240:241]
	v_pk_mul_f32 v[48:49], v[48:49], v[238:239]
	v_pk_mul_f32 v[50:51], v[50:51], v[240:241]
	v_pk_mul_f32 v[52:53], v[52:53], v[238:239]
	v_pk_mul_f32 v[54:55], v[54:55], v[240:241]
	v_pk_mul_f32 v[56:57], v[56:57], v[238:239]
	v_pk_mul_f32 v[58:59], v[58:59], v[240:241]
	v_pk_mul_f32 v[60:61], v[60:61], v[238:239]
	v_pk_mul_f32 v[62:63], v[62:63], v[240:241]
	ds_write2_b32 v200, v32, v33 offset0:0 offset1:132
	ds_write2_b32 v201, v34, v35 offset0:0 offset1:132
	ds_write2_b32 v200, v36, v37 offset0:16 offset1:148
	ds_write2_b32 v201, v38, v39 offset0:16 offset1:148
	ds_write2_b32 v200, v40, v41 offset0:32 offset1:164
	ds_write2_b32 v201, v42, v43 offset0:32 offset1:164
	ds_write2_b32 v200, v44, v45 offset0:48 offset1:180
	ds_write2_b32 v201, v46, v47 offset0:48 offset1:180
	ds_write2_b32 v200, v48, v49 offset0:64 offset1:196
	ds_write2_b32 v201, v50, v51 offset0:64 offset1:196
	ds_write2_b32 v200, v52, v53 offset0:80 offset1:212
	ds_write2_b32 v201, v54, v55 offset0:80 offset1:212
	ds_write2_b32 v200, v56, v57 offset0:96 offset1:228
	ds_write2_b32 v201, v58, v59 offset0:96 offset1:228
	ds_write2_b32 v200, v60, v61 offset0:112 offset1:244
	ds_write2_b32 v201, v62, v63 offset0:112 offset1:244
	s_waitcnt lgkmcnt(0)
	ds_read_b128 v[0:3], v202
	ds_read_b128 v[4:7], v202 offset:1056
	ds_read_b128 v[8:11], v202 offset:2112
	ds_read_b128 v[12:15], v202 offset:3168
	ds_read_b128 v[16:19], v202 offset:4224
	ds_read_b128 v[20:23], v202 offset:5280
	ds_read_b128 v[24:27], v202 offset:6336
	ds_read_b128 v[28:31], v202 offset:7392
	ds_read_b128 v[32:35], v202 offset:8448
	s_waitcnt lgkmcnt(8)
	v_lshl_add_u64 v[206:207], v[204:205], 0, s[8:9]
	v_cvt_pk_bf16_f32 v0, v0, v1
	v_cvt_pk_bf16_f32 v1, v2, v3
	s_add_u32 s8, s8, s4
	s_addc_u32 s9, s9, 0
	global_store_dwordx2 v[206:207], v[0:1], off
	ds_read_b128 v[36:39], v202 offset:9504
	s_waitcnt lgkmcnt(8)
	v_lshl_add_u64 v[206:207], v[204:205], 0, s[8:9]
	v_cvt_pk_bf16_f32 v4, v4, v5
	v_cvt_pk_bf16_f32 v5, v6, v7
	s_add_u32 s8, s8, s4
	s_addc_u32 s9, s9, 0
	global_store_dwordx2 v[206:207], v[4:5], off
	ds_read_b128 v[40:43], v202 offset:10560
	s_waitcnt lgkmcnt(8)
	v_lshl_add_u64 v[206:207], v[204:205], 0, s[8:9]
	v_cvt_pk_bf16_f32 v8, v8, v9
	v_cvt_pk_bf16_f32 v9, v10, v11
	s_add_u32 s8, s8, s4
	s_addc_u32 s9, s9, 0
	global_store_dwordx2 v[206:207], v[8:9], off
	ds_read_b128 v[44:47], v202 offset:11616
	s_waitcnt lgkmcnt(8)
	v_lshl_add_u64 v[206:207], v[204:205], 0, s[8:9]
	v_cvt_pk_bf16_f32 v12, v12, v13
	v_cvt_pk_bf16_f32 v13, v14, v15
	s_add_u32 s8, s8, s4
	s_addc_u32 s9, s9, 0
	global_store_dwordx2 v[206:207], v[12:13], off
	ds_read_b128 v[48:51], v202 offset:12672
	s_waitcnt lgkmcnt(8)
	v_lshl_add_u64 v[206:207], v[204:205], 0, s[8:9]
	v_cvt_pk_bf16_f32 v16, v16, v17
	v_cvt_pk_bf16_f32 v17, v18, v19
	s_add_u32 s8, s8, s4
	s_addc_u32 s9, s9, 0
	global_store_dwordx2 v[206:207], v[16:17], off
	ds_read_b128 v[52:55], v202 offset:13728
	s_waitcnt lgkmcnt(8)
	v_lshl_add_u64 v[206:207], v[204:205], 0, s[8:9]
	v_cvt_pk_bf16_f32 v20, v20, v21
	v_cvt_pk_bf16_f32 v21, v22, v23
	s_add_u32 s8, s8, s4
	s_addc_u32 s9, s9, 0
	global_store_dwordx2 v[206:207], v[20:21], off
	ds_read_b128 v[56:59], v202 offset:14784
	s_waitcnt lgkmcnt(8)
	v_lshl_add_u64 v[206:207], v[204:205], 0, s[8:9]
	v_cvt_pk_bf16_f32 v24, v24, v25
	v_cvt_pk_bf16_f32 v25, v26, v27
	s_add_u32 s8, s8, s4
	s_addc_u32 s9, s9, 0
	global_store_dwordx2 v[206:207], v[24:25], off
	ds_read_b128 v[60:63], v202 offset:15840
	s_waitcnt lgkmcnt(8)
	v_lshl_add_u64 v[206:207], v[204:205], 0, s[8:9]
	v_cvt_pk_bf16_f32 v28, v28, v29
	v_cvt_pk_bf16_f32 v29, v30, v31
	s_add_u32 s8, s8, s4
	s_addc_u32 s9, s9, 0
	global_store_dwordx2 v[206:207], v[28:29], off
	s_waitcnt lgkmcnt(7)
	v_lshl_add_u64 v[206:207], v[204:205], 0, s[8:9]
	v_cvt_pk_bf16_f32 v32, v32, v33
	v_cvt_pk_bf16_f32 v33, v34, v35
	s_add_u32 s8, s8, s4
	s_addc_u32 s9, s9, 0
	global_store_dwordx2 v[206:207], v[32:33], off
	s_waitcnt lgkmcnt(6)
	v_lshl_add_u64 v[206:207], v[204:205], 0, s[8:9]
	v_cvt_pk_bf16_f32 v36, v36, v37
	v_cvt_pk_bf16_f32 v37, v38, v39
	s_add_u32 s8, s8, s4
	s_addc_u32 s9, s9, 0
	global_store_dwordx2 v[206:207], v[36:37], off
	s_waitcnt lgkmcnt(5)
	v_lshl_add_u64 v[206:207], v[204:205], 0, s[8:9]
	v_cvt_pk_bf16_f32 v40, v40, v41
	v_cvt_pk_bf16_f32 v41, v42, v43
	s_add_u32 s8, s8, s4
	s_addc_u32 s9, s9, 0
	global_store_dwordx2 v[206:207], v[40:41], off
	s_waitcnt lgkmcnt(4)
	v_lshl_add_u64 v[206:207], v[204:205], 0, s[8:9]
	v_cvt_pk_bf16_f32 v44, v44, v45
	v_cvt_pk_bf16_f32 v45, v46, v47
	s_add_u32 s8, s8, s4
	s_addc_u32 s9, s9, 0
	global_store_dwordx2 v[206:207], v[44:45], off
	s_waitcnt lgkmcnt(3)
	v_lshl_add_u64 v[206:207], v[204:205], 0, s[8:9]
	v_cvt_pk_bf16_f32 v48, v48, v49
	v_cvt_pk_bf16_f32 v49, v50, v51
	s_add_u32 s8, s8, s4
	s_addc_u32 s9, s9, 0
	global_store_dwordx2 v[206:207], v[48:49], off
	s_waitcnt lgkmcnt(2)
	v_lshl_add_u64 v[206:207], v[204:205], 0, s[8:9]
	v_cvt_pk_bf16_f32 v52, v52, v53
	v_cvt_pk_bf16_f32 v53, v54, v55
	s_add_u32 s8, s8, s4
	s_addc_u32 s9, s9, 0
	global_store_dwordx2 v[206:207], v[52:53], off
	s_waitcnt lgkmcnt(1)
	v_lshl_add_u64 v[206:207], v[204:205], 0, s[8:9]
	v_cvt_pk_bf16_f32 v56, v56, v57
	v_cvt_pk_bf16_f32 v57, v58, v59
	s_add_u32 s8, s8, s4
	s_addc_u32 s9, s9, 0
	global_store_dwordx2 v[206:207], v[56:57], off
	s_waitcnt lgkmcnt(0)
	v_lshl_add_u64 v[206:207], v[204:205], 0, s[8:9]
	v_cvt_pk_bf16_f32 v60, v60, v61
	v_cvt_pk_bf16_f32 v61, v62, v63
	s_add_u32 s8, s8, s4
	s_addc_u32 s9, s9, 0
	global_store_dwordx2 v[206:207], v[60:61], off
	s_branch .LBB0_108
